# v022 minus the 36 redundant back-to-back duplicate s_waitcnt lgkmcnt(0) at the heads of the GEMM compute segments (left adjacent after the s_setprio toggles were deleted)
# baseline (speedup 1.0000x reference)
.LBB0_127:
	ds_read_b128 v[176:179], v167
	ds_read_b128 v[180:183], v167 offset:1024
	ds_read_b128 v[186:189], v167 offset:2048
	ds_read_b128 v[190:193], v167 offset:3072
	s_add_u32 s40, s38, 0xfff00080
	s_addc_u32 s41, s39, -1
	s_cmp_eq_u32 s54, 60
	s_cselect_b32 s43, s6, s41
	s_cselect_b32 s42, s7, s40
	s_cselect_b32 s41, s9, s29
	s_cselect_b32 s40, s11, s27
	v_lshl_add_u64 v[156:157], s[38:39], 0, v[138:139]
	s_add_i32 m0, s44, 0xc000
	ds_read_b128 v[194:197], v168
	ds_read_b128 v[198:201], v168 offset:1024
	ds_read_b128 v[202:205], v168 offset:2048
	ds_read_b128 v[206:209], v168 offset:3072
	ds_read_b128 v[210:213], v168 offset:4096
	ds_read_b128 v[214:217], v168 offset:5120
	ds_read_b128 v[218:221], v168 offset:6144
	ds_read_b128 v[222:225], v168 offset:7168
	global_load_lds_dwordx4 v[156:157], off
	v_lshl_add_u64 v[156:157], s[38:39], 0, v[140:141]
	s_add_i32 m0, s44, 0xe000
	s_nop 0
	global_load_lds_dwordx4 v[156:157], off
	s_waitcnt lgkmcnt(8)
	s_barrier
	s_waitcnt lgkmcnt(0)
	v_mfma_f32_16x16x32_bf16 v[124:127], v[176:179], v[194:197], v[124:127]
	v_mfma_f32_16x16x32_bf16 v[124:127], v[180:183], v[198:201], v[124:127]
	v_mfma_f32_16x16x32_bf16 v[120:123], v[186:189], v[194:197], v[120:123]
	v_mfma_f32_16x16x32_bf16 v[120:123], v[190:193], v[198:201], v[120:123]
	v_mfma_f32_16x16x32_bf16 v[108:111], v[176:179], v[202:205], v[108:111]
	v_mfma_f32_16x16x32_bf16 v[108:111], v[180:183], v[206:209], v[108:111]
	v_mfma_f32_16x16x32_bf16 v[104:107], v[186:189], v[202:205], v[104:107]
	v_mfma_f32_16x16x32_bf16 v[104:107], v[190:193], v[206:209], v[104:107]
	v_mfma_f32_16x16x32_bf16 v[92:95], v[176:179], v[210:213], v[92:95]
	v_mfma_f32_16x16x32_bf16 v[92:95], v[180:183], v[214:217], v[92:95]
	v_mfma_f32_16x16x32_bf16 v[88:91], v[186:189], v[210:213], v[88:91]
	v_mfma_f32_16x16x32_bf16 v[88:91], v[190:193], v[214:217], v[88:91]
	v_mfma_f32_16x16x32_bf16 v[76:79], v[176:179], v[218:221], v[76:79]
	v_mfma_f32_16x16x32_bf16 v[76:79], v[180:183], v[222:225], v[76:79]
	v_mfma_f32_16x16x32_bf16 v[72:75], v[186:189], v[218:221], v[72:75]
	v_mfma_f32_16x16x32_bf16 v[72:75], v[190:193], v[222:225], v[72:75]
	s_barrier
	s_add_i32 s55, s72, s5
	v_lshl_add_u64 v[156:157], s[40:41], 0, v[130:131]
	s_mov_b32 m0, s55
	ds_read_b128 v[226:229], v169
	ds_read_b128 v[230:233], v169 offset:1024
	ds_read_b128 v[234:237], v169 offset:2048
	ds_read_b128 v[238:241], v169 offset:3072
	global_load_lds_dwordx4 v[156:157], off
	v_lshl_add_u64 v[162:163], s[40:41], 0, v[134:135]
	s_add_i32 m0, s55, 0x2000
	s_nop 0
	global_load_lds_dwordx4 v[162:163], off
	s_barrier
	s_waitcnt lgkmcnt(0)
	v_mfma_f32_16x16x32_bf16 v[116:119], v[226:229], v[194:197], v[116:119]
	v_mfma_f32_16x16x32_bf16 v[116:119], v[230:233], v[198:201], v[116:119]
	v_mfma_f32_16x16x32_bf16 v[112:115], v[234:237], v[194:197], v[112:115]
	v_mfma_f32_16x16x32_bf16 v[112:115], v[238:241], v[198:201], v[112:115]
	v_mfma_f32_16x16x32_bf16 v[100:103], v[226:229], v[202:205], v[100:103]
	v_mfma_f32_16x16x32_bf16 v[100:103], v[230:233], v[206:209], v[100:103]
	v_mfma_f32_16x16x32_bf16 v[96:99], v[234:237], v[202:205], v[96:99]
	v_mfma_f32_16x16x32_bf16 v[96:99], v[238:241], v[206:209], v[96:99]
	v_mfma_f32_16x16x32_bf16 v[84:87], v[226:229], v[210:213], v[84:87]
	v_mfma_f32_16x16x32_bf16 v[84:87], v[230:233], v[214:217], v[84:87]
	v_mfma_f32_16x16x32_bf16 v[80:83], v[234:237], v[210:213], v[80:83]
	v_mfma_f32_16x16x32_bf16 v[80:83], v[238:241], v[214:217], v[80:83]
	v_mfma_f32_16x16x32_bf16 v[68:71], v[226:229], v[218:221], v[68:71]
	v_mfma_f32_16x16x32_bf16 v[68:71], v[230:233], v[222:225], v[68:71]
	v_mfma_f32_16x16x32_bf16 v[64:67], v[234:237], v[218:221], v[64:67]
	v_mfma_f32_16x16x32_bf16 v[64:67], v[238:241], v[222:225], v[64:67]
	s_mov_b32 m0, s44
	v_lshl_add_u64 v[170:171], s[42:43], 0, v[128:129]
	s_barrier
	ds_read_b128 v[194:197], v168 offset:16384
	ds_read_b128 v[198:201], v168 offset:17408
	ds_read_b128 v[202:205], v168 offset:18432
	ds_read_b128 v[206:209], v168 offset:19456
	ds_read_b128 v[210:213], v168 offset:20480
	ds_read_b128 v[214:217], v168 offset:21504
	ds_read_b128 v[218:221], v168 offset:22528
	ds_read_b128 v[222:225], v168 offset:23552
	global_load_lds_dwordx4 v[170:171], off
	v_lshl_add_u64 v[242:243], s[42:43], 0, v[132:133]
	s_mov_b32 m0, s45
	s_nop 0
	global_load_lds_dwordx4 v[242:243], off
	s_barrier
	s_waitcnt lgkmcnt(0)
	v_mfma_f32_16x16x32_bf16 v[60:63], v[176:179], v[194:197], v[60:63]
	v_mfma_f32_16x16x32_bf16 v[60:63], v[180:183], v[198:201], v[60:63]
	v_mfma_f32_16x16x32_bf16 v[56:59], v[186:189], v[194:197], v[56:59]
	v_mfma_f32_16x16x32_bf16 v[56:59], v[190:193], v[198:201], v[56:59]
	v_mfma_f32_16x16x32_bf16 v[44:47], v[176:179], v[202:205], v[44:47]
	v_mfma_f32_16x16x32_bf16 v[44:47], v[180:183], v[206:209], v[44:47]
	v_mfma_f32_16x16x32_bf16 v[40:43], v[186:189], v[202:205], v[40:43]
	v_mfma_f32_16x16x32_bf16 v[40:43], v[190:193], v[206:209], v[40:43]
	v_mfma_f32_16x16x32_bf16 v[28:31], v[176:179], v[210:213], v[28:31]
	v_mfma_f32_16x16x32_bf16 v[28:31], v[180:183], v[214:217], v[28:31]
	v_mfma_f32_16x16x32_bf16 v[24:27], v[186:189], v[210:213], v[24:27]
	v_mfma_f32_16x16x32_bf16 v[24:27], v[190:193], v[214:217], v[24:27]
	v_mfma_f32_16x16x32_bf16 v[12:15], v[176:179], v[218:221], v[12:15]
	v_mfma_f32_16x16x32_bf16 v[12:15], v[180:183], v[222:225], v[12:15]
	v_mfma_f32_16x16x32_bf16 v[8:11], v[186:189], v[218:221], v[8:11]
	v_mfma_f32_16x16x32_bf16 v[8:11], v[190:193], v[222:225], v[8:11]
	s_barrier
	s_add_u32 s62, s40, 0x100000
	s_addc_u32 s63, s41, 0
	s_add_i32 s55, s73, s5
	v_lshl_add_u64 v[176:177], s[62:63], 0, v[130:131]
	s_mov_b32 m0, s55
	s_nop 0
	global_load_lds_dwordx4 v[176:177], off
	v_lshl_add_u64 v[176:177], s[62:63], 0, v[134:135]
	s_add_i32 m0, s55, 0x2000
	s_nop 0
	global_load_lds_dwordx4 v[176:177], off
	s_waitcnt vmcnt(6)
	s_barrier
	v_mfma_f32_16x16x32_bf16 v[52:55], v[226:229], v[194:197], v[52:55]
	v_mfma_f32_16x16x32_bf16 v[52:55], v[230:233], v[198:201], v[52:55]
	v_mfma_f32_16x16x32_bf16 v[48:51], v[234:237], v[194:197], v[48:51]
	v_mfma_f32_16x16x32_bf16 v[48:51], v[238:241], v[198:201], v[48:51]
	v_mfma_f32_16x16x32_bf16 v[36:39], v[226:229], v[202:205], v[36:39]
	v_mfma_f32_16x16x32_bf16 v[36:39], v[230:233], v[206:209], v[36:39]
	v_mfma_f32_16x16x32_bf16 v[32:35], v[234:237], v[202:205], v[32:35]
	v_mfma_f32_16x16x32_bf16 v[32:35], v[238:241], v[206:209], v[32:35]
	v_mfma_f32_16x16x32_bf16 v[20:23], v[226:229], v[210:213], v[20:23]
	v_mfma_f32_16x16x32_bf16 v[20:23], v[230:233], v[214:217], v[20:23]
	v_mfma_f32_16x16x32_bf16 v[16:19], v[234:237], v[210:213], v[16:19]
	v_mfma_f32_16x16x32_bf16 v[16:19], v[238:241], v[214:217], v[16:19]
	v_mfma_f32_16x16x32_bf16 v[4:7], v[226:229], v[218:221], v[4:7]
	v_mfma_f32_16x16x32_bf16 v[4:7], v[230:233], v[222:225], v[4:7]
	v_mfma_f32_16x16x32_bf16 v[0:3], v[234:237], v[218:221], v[0:3]
	v_mfma_f32_16x16x32_bf16 v[0:3], v[238:241], v[222:225], v[0:3]
	s_add_i32 s55, 0, 0x18000
	v_add_u32_e32 v137, s55, v165
	s_barrier
	ds_read_b128 v[176:179], v137
	ds_read_b128 v[180:183], v137 offset:1024
	ds_read_b128 v[186:189], v137 offset:2048
	ds_read_b128 v[190:193], v137 offset:3072
	s_add_u32 s42, s42, 0x100000
	s_addc_u32 s43, s43, 0
	s_mov_b32 m0, s46
	v_lshl_add_u64 v[226:227], s[42:43], 0, v[128:129]
	ds_read_b128 v[194:197], v168 offset:32768
	ds_read_b128 v[198:201], v168 offset:33792
	ds_read_b128 v[202:205], v168 offset:34816
	ds_read_b128 v[206:209], v168 offset:35840
	ds_read_b128 v[210:213], v168 offset:36864
	ds_read_b128 v[214:217], v168 offset:37888
	ds_read_b128 v[218:221], v168 offset:38912
	ds_read_b128 v[222:225], v168 offset:39936
	global_load_lds_dwordx4 v[226:227], off
	v_lshl_add_u64 v[226:227], s[42:43], 0, v[132:133]
	s_mov_b32 m0, s47
	s_nop 0
	global_load_lds_dwordx4 v[226:227], off
	s_waitcnt lgkmcnt(8)
	s_barrier
	s_waitcnt lgkmcnt(0)
	v_mfma_f32_16x16x32_bf16 v[124:127], v[176:179], v[194:197], v[124:127]
	v_mfma_f32_16x16x32_bf16 v[124:127], v[180:183], v[198:201], v[124:127]
	v_mfma_f32_16x16x32_bf16 v[120:123], v[186:189], v[194:197], v[120:123]
	v_mfma_f32_16x16x32_bf16 v[120:123], v[190:193], v[198:201], v[120:123]
	v_mfma_f32_16x16x32_bf16 v[108:111], v[176:179], v[202:205], v[108:111]
	v_mfma_f32_16x16x32_bf16 v[108:111], v[180:183], v[206:209], v[108:111]
	v_mfma_f32_16x16x32_bf16 v[104:107], v[186:189], v[202:205], v[104:107]
	v_mfma_f32_16x16x32_bf16 v[104:107], v[190:193], v[206:209], v[104:107]
	v_mfma_f32_16x16x32_bf16 v[92:95], v[176:179], v[210:213], v[92:95]
	v_mfma_f32_16x16x32_bf16 v[92:95], v[180:183], v[214:217], v[92:95]
	v_mfma_f32_16x16x32_bf16 v[88:91], v[186:189], v[210:213], v[88:91]
	v_mfma_f32_16x16x32_bf16 v[88:91], v[190:193], v[214:217], v[88:91]
	v_mfma_f32_16x16x32_bf16 v[76:79], v[176:179], v[218:221], v[76:79]
	v_mfma_f32_16x16x32_bf16 v[76:79], v[180:183], v[222:225], v[76:79]
	v_mfma_f32_16x16x32_bf16 v[72:75], v[186:189], v[218:221], v[72:75]
	v_mfma_f32_16x16x32_bf16 v[72:75], v[190:193], v[222:225], v[72:75]
	s_barrier
	s_add_i32 s42, 0, 0x1c000
	s_add_i32 s43, s55, s5
	v_add_u32_e32 v137, s42, v165
	v_lshl_add_u64 v[156:157], v[156:157], 0, s[24:25]
	s_mov_b32 m0, s43
	ds_read_b128 v[226:229], v137
	ds_read_b128 v[230:233], v137 offset:1024
	ds_read_b128 v[234:237], v137 offset:2048
	ds_read_b128 v[238:241], v137 offset:3072
	global_load_lds_dwordx4 v[156:157], off
	v_lshl_add_u64 v[156:157], v[162:163], 0, s[24:25]
	s_add_i32 m0, s43, 0x2000
	s_nop 0
	global_load_lds_dwordx4 v[156:157], off
	s_barrier
	s_waitcnt lgkmcnt(0)
	v_mfma_f32_16x16x32_bf16 v[116:119], v[226:229], v[194:197], v[116:119]
	v_mfma_f32_16x16x32_bf16 v[116:119], v[230:233], v[198:201], v[116:119]
	v_mfma_f32_16x16x32_bf16 v[112:115], v[234:237], v[194:197], v[112:115]
	v_mfma_f32_16x16x32_bf16 v[112:115], v[238:241], v[198:201], v[112:115]
	v_mfma_f32_16x16x32_bf16 v[100:103], v[226:229], v[202:205], v[100:103]
	v_mfma_f32_16x16x32_bf16 v[100:103], v[230:233], v[206:209], v[100:103]
	v_mfma_f32_16x16x32_bf16 v[96:99], v[234:237], v[202:205], v[96:99]
	v_mfma_f32_16x16x32_bf16 v[96:99], v[238:241], v[206:209], v[96:99]
	v_mfma_f32_16x16x32_bf16 v[84:87], v[226:229], v[210:213], v[84:87]
	v_mfma_f32_16x16x32_bf16 v[84:87], v[230:233], v[214:217], v[84:87]
	v_mfma_f32_16x16x32_bf16 v[80:83], v[234:237], v[210:213], v[80:83]
	v_mfma_f32_16x16x32_bf16 v[80:83], v[238:241], v[214:217], v[80:83]
	v_mfma_f32_16x16x32_bf16 v[68:71], v[226:229], v[218:221], v[68:71]
	v_mfma_f32_16x16x32_bf16 v[68:71], v[230:233], v[222:225], v[68:71]
	v_mfma_f32_16x16x32_bf16 v[64:67], v[234:237], v[218:221], v[64:67]
	v_mfma_f32_16x16x32_bf16 v[64:67], v[238:241], v[222:225], v[64:67]
	s_mov_b32 m0, s49
	v_lshl_add_u64 v[156:157], v[170:171], 0, s[24:25]
	s_barrier
	ds_read_b128 v[194:197], v168 offset:49152
	ds_read_b128 v[198:201], v168 offset:50176
	ds_read_b128 v[202:205], v168 offset:51200
	ds_read_b128 v[206:209], v168 offset:52224
	ds_read_b128 v[210:213], v168 offset:53248
	ds_read_b128 v[214:217], v168 offset:54272
	ds_read_b128 v[218:221], v168 offset:55296
	ds_read_b128 v[222:225], v168 offset:56320
	global_load_lds_dwordx4 v[156:157], off
	v_lshl_add_u64 v[156:157], v[242:243], 0, s[24:25]
	s_mov_b32 m0, s50
	s_nop 0
	global_load_lds_dwordx4 v[156:157], off
	s_barrier
	s_waitcnt lgkmcnt(0)
	v_mfma_f32_16x16x32_bf16 v[60:63], v[176:179], v[194:197], v[60:63]
	v_mfma_f32_16x16x32_bf16 v[60:63], v[180:183], v[198:201], v[60:63]
	v_mfma_f32_16x16x32_bf16 v[56:59], v[186:189], v[194:197], v[56:59]
	v_mfma_f32_16x16x32_bf16 v[56:59], v[190:193], v[198:201], v[56:59]
	v_mfma_f32_16x16x32_bf16 v[44:47], v[176:179], v[202:205], v[44:47]
	v_mfma_f32_16x16x32_bf16 v[44:47], v[180:183], v[206:209], v[44:47]
	v_mfma_f32_16x16x32_bf16 v[40:43], v[186:189], v[202:205], v[40:43]
	v_mfma_f32_16x16x32_bf16 v[40:43], v[190:193], v[206:209], v[40:43]
	v_mfma_f32_16x16x32_bf16 v[28:31], v[176:179], v[210:213], v[28:31]
	v_mfma_f32_16x16x32_bf16 v[28:31], v[180:183], v[214:217], v[28:31]
	v_mfma_f32_16x16x32_bf16 v[24:27], v[186:189], v[210:213], v[24:27]
	v_mfma_f32_16x16x32_bf16 v[24:27], v[190:193], v[214:217], v[24:27]
	v_mfma_f32_16x16x32_bf16 v[12:15], v[176:179], v[218:221], v[12:15]
	v_mfma_f32_16x16x32_bf16 v[12:15], v[180:183], v[222:225], v[12:15]
	v_mfma_f32_16x16x32_bf16 v[8:11], v[186:189], v[218:221], v[8:11]
	v_mfma_f32_16x16x32_bf16 v[8:11], v[190:193], v[222:225], v[8:11]
	s_barrier
	s_add_u32 s40, s40, 0x100080
	s_addc_u32 s41, s41, 0
	s_add_i32 s42, s42, s5
	v_lshl_add_u64 v[156:157], s[40:41], 0, v[130:131]
	s_mov_b32 m0, s42
	s_nop 0
	global_load_lds_dwordx4 v[156:157], off
	v_lshl_add_u64 v[156:157], s[40:41], 0, v[134:135]
	s_add_i32 m0, s42, 0x2000
	s_nop 0
	global_load_lds_dwordx4 v[156:157], off
	s_waitcnt vmcnt(6)
	s_barrier
	v_mfma_f32_16x16x32_bf16 v[52:55], v[226:229], v[194:197], v[52:55]
	v_mfma_f32_16x16x32_bf16 v[52:55], v[230:233], v[198:201], v[52:55]
	v_mfma_f32_16x16x32_bf16 v[48:51], v[234:237], v[194:197], v[48:51]
	v_mfma_f32_16x16x32_bf16 v[48:51], v[238:241], v[198:201], v[48:51]
	v_mfma_f32_16x16x32_bf16 v[36:39], v[226:229], v[202:205], v[36:39]
	v_mfma_f32_16x16x32_bf16 v[36:39], v[230:233], v[206:209], v[36:39]
	v_mfma_f32_16x16x32_bf16 v[32:35], v[234:237], v[202:205], v[32:35]
	v_mfma_f32_16x16x32_bf16 v[32:35], v[238:241], v[206:209], v[32:35]
	v_mfma_f32_16x16x32_bf16 v[20:23], v[226:229], v[210:213], v[20:23]
	v_mfma_f32_16x16x32_bf16 v[20:23], v[230:233], v[214:217], v[20:23]
	v_mfma_f32_16x16x32_bf16 v[16:19], v[234:237], v[210:213], v[16:19]
	v_mfma_f32_16x16x32_bf16 v[16:19], v[238:241], v[214:217], v[16:19]
	v_mfma_f32_16x16x32_bf16 v[4:7], v[226:229], v[218:221], v[4:7]
	v_mfma_f32_16x16x32_bf16 v[4:7], v[230:233], v[222:225], v[4:7]
	v_mfma_f32_16x16x32_bf16 v[0:3], v[234:237], v[218:221], v[0:3]
	v_mfma_f32_16x16x32_bf16 v[0:3], v[238:241], v[222:225], v[0:3]
	s_add_i32 s54, s54, 2
	s_add_u32 s38, s38, 0x100
	s_addc_u32 s39, s39, 0
	s_add_u32 s27, s27, 0x100
	s_addc_u32 s29, s29, 0
	s_cmp_gt_u32 s54, 61
	s_barrier
	s_cbranch_scc0 .LBB0_127
	v_lshl_or_b32 v156, s8, 8, v166
	s_waitcnt vmcnt(0)
	v_pk_mul_f32 v[126:127], v[160:161], v[126:127] op_sel_hi:[0,1]
	v_pk_mul_f32 v[124:125], v[160:161], v[124:125] op_sel_hi:[0,1]
	v_pk_mul_f32 v[122:123], v[160:161], v[122:123] op_sel_hi:[0,1]
	v_pk_mul_f32 v[162:163], v[160:161], v[120:121] op_sel_hi:[0,1]
	v_cmp_lt_i32_e64 s[8:9], s74, v156
	s_and_saveexec_b64 s[38:39], s[8:9]
	s_cbranch_execz .LBB0_130
	v_mul_f32_e32 v147, 0xbfb8aa3b, v126
	v_mul_f32_e32 v121, 0xbfb8aa3b, v162
	v_exp_f32_e32 v147, v147
	v_mul_f32_e32 v149, 0xbfb8aa3b, v122
	v_mul_f32_e32 v137, 0xbfb8aa3b, v125
	v_exp_f32_e32 v121, v121
	v_exp_f32_e32 v149, v149
	v_exp_f32_e32 v137, v137
	v_add_f32_e32 v147, 1.0, v147
	v_add_f32_e32 v121, 1.0, v121
	v_rcp_f32_e32 v176, v147
	v_add_f32_e32 v147, 1.0, v149
	v_mul_f32_e32 v149, 0xbfb8aa3b, v127
	v_mul_f32_e32 v120, 0xbfb8aa3b, v124
	v_rcp_f32_e32 v170, v121
	v_add_f32_e32 v121, 1.0, v137
	v_mul_f32_e32 v137, 0xbfb8aa3b, v163
	v_exp_f32_e32 v149, v149
	v_mul_f32_e32 v151, 0xbfb8aa3b, v123
	v_exp_f32_e32 v120, v120
	v_exp_f32_e32 v137, v137
	v_exp_f32_e32 v151, v151
	v_rcp_f32_e32 v178, v147
	v_add_f32_e32 v147, 1.0, v149
	v_add_f32_e32 v120, 1.0, v120
	v_add_f32_e32 v137, 1.0, v137
	v_rcp_f32_e32 v177, v147
	v_add_f32_e32 v147, 1.0, v151
	v_rcp_f32_e32 v120, v120
	v_rcp_f32_e32 v121, v121
	v_rcp_f32_e32 v179, v147
	v_rcp_f32_e32 v171, v137
	v_pk_mul_f32 v[126:127], v[126:127], v[176:177]
	v_pk_mul_f32 v[124:125], v[124:125], v[120:121]
	v_pk_mul_f32 v[122:123], v[122:123], v[178:179]
	v_pk_mul_f32 v[162:163], v[162:163], v[170:171]

.LBB0_301:
	ds_read_b128 v[160:163], v151
	ds_read_b128 v[164:167], v151 offset:1024
	ds_read_b128 v[168:171], v151 offset:2048
	ds_read_b128 v[176:179], v151 offset:3072
	s_add_u32 s44, s42, 0x100
	s_addc_u32 s45, s43, 0
	s_cmp_eq_u32 s83, 12
	s_cselect_b32 s49, s39, s45
	s_cselect_b32 s48, s38, s44
	s_cselect_b32 s47, s37, s82
	s_cselect_b32 s46, s62, s63
	v_lshl_add_u64 v[214:215], s[42:43], 0, v[142:143]
	s_add_i32 m0, s50, 0xc000
	ds_read_b128 v[180:183], v153
	ds_read_b128 v[186:189], v153 offset:1024
	ds_read_b128 v[190:193], v153 offset:2048
	ds_read_b128 v[194:197], v153 offset:3072
	ds_read_b128 v[198:201], v153 offset:4096
	ds_read_b128 v[202:205], v153 offset:5120
	ds_read_b128 v[206:209], v153 offset:6144
	ds_read_b128 v[210:213], v153 offset:7168
	global_load_lds_dwordx4 v[214:215], off
	v_lshl_add_u64 v[214:215], s[42:43], 0, v[144:145]
	s_add_i32 m0, s50, 0xe000
	s_nop 0
	global_load_lds_dwordx4 v[214:215], off
	s_waitcnt lgkmcnt(8)
	s_barrier
	s_waitcnt lgkmcnt(0)
	v_mfma_f32_16x16x32_bf16 v[124:127], v[160:163], v[180:183], v[124:127]
	v_mfma_f32_16x16x32_bf16 v[124:127], v[164:167], v[186:189], v[124:127]
	v_mfma_f32_16x16x32_bf16 v[120:123], v[168:171], v[180:183], v[120:123]
	v_mfma_f32_16x16x32_bf16 v[120:123], v[176:179], v[186:189], v[120:123]
	v_mfma_f32_16x16x32_bf16 v[112:115], v[160:163], v[190:193], v[112:115]
	v_mfma_f32_16x16x32_bf16 v[112:115], v[164:167], v[194:197], v[112:115]
	v_mfma_f32_16x16x32_bf16 v[104:107], v[168:171], v[190:193], v[104:107]
	v_mfma_f32_16x16x32_bf16 v[104:107], v[176:179], v[194:197], v[104:107]
	v_mfma_f32_16x16x32_bf16 v[96:99], v[160:163], v[198:201], v[96:99]
	v_mfma_f32_16x16x32_bf16 v[96:99], v[164:167], v[202:205], v[96:99]
	v_mfma_f32_16x16x32_bf16 v[88:91], v[168:171], v[198:201], v[88:91]
	v_mfma_f32_16x16x32_bf16 v[88:91], v[176:179], v[202:205], v[88:91]
	v_mfma_f32_16x16x32_bf16 v[80:83], v[160:163], v[206:209], v[80:83]
	v_mfma_f32_16x16x32_bf16 v[80:83], v[164:167], v[210:213], v[80:83]
	v_mfma_f32_16x16x32_bf16 v[72:75], v[168:171], v[206:209], v[72:75]
	v_mfma_f32_16x16x32_bf16 v[72:75], v[176:179], v[210:213], v[72:75]
	s_barrier
	s_add_i32 s42, s76, s5
	v_lshl_add_u64 v[230:231], s[46:47], 0, v[132:133]
	s_mov_b32 m0, s42
	ds_read_b128 v[214:217], v155
	ds_read_b128 v[218:221], v155 offset:1024
	ds_read_b128 v[222:225], v155 offset:2048
	ds_read_b128 v[226:229], v155 offset:3072
	global_load_lds_dwordx4 v[230:231], off
	v_lshl_add_u64 v[232:233], s[46:47], 0, v[128:129]
	s_add_i32 m0, s42, 0x2000
	s_nop 0
	global_load_lds_dwordx4 v[232:233], off
	s_barrier
	s_waitcnt lgkmcnt(0)
	v_mfma_f32_16x16x32_bf16 v[116:119], v[214:217], v[180:183], v[116:119]
	v_mfma_f32_16x16x32_bf16 v[116:119], v[218:221], v[186:189], v[116:119]
	v_mfma_f32_16x16x32_bf16 v[108:111], v[222:225], v[180:183], v[108:111]
	v_mfma_f32_16x16x32_bf16 v[108:111], v[226:229], v[186:189], v[108:111]
	v_mfma_f32_16x16x32_bf16 v[100:103], v[214:217], v[190:193], v[100:103]
	v_mfma_f32_16x16x32_bf16 v[100:103], v[218:221], v[194:197], v[100:103]
	v_mfma_f32_16x16x32_bf16 v[92:95], v[222:225], v[190:193], v[92:95]
	v_mfma_f32_16x16x32_bf16 v[92:95], v[226:229], v[194:197], v[92:95]
	v_mfma_f32_16x16x32_bf16 v[84:87], v[214:217], v[198:201], v[84:87]
	v_mfma_f32_16x16x32_bf16 v[84:87], v[218:221], v[202:205], v[84:87]
	v_mfma_f32_16x16x32_bf16 v[76:79], v[222:225], v[198:201], v[76:79]
	v_mfma_f32_16x16x32_bf16 v[76:79], v[226:229], v[202:205], v[76:79]
	v_mfma_f32_16x16x32_bf16 v[68:71], v[214:217], v[206:209], v[68:71]
	v_mfma_f32_16x16x32_bf16 v[68:71], v[218:221], v[210:213], v[68:71]
	v_mfma_f32_16x16x32_bf16 v[64:67], v[222:225], v[206:209], v[64:67]
	v_mfma_f32_16x16x32_bf16 v[64:67], v[226:229], v[210:213], v[64:67]
	s_mov_b32 m0, s50
	v_lshl_add_u64 v[234:235], s[48:49], 0, v[134:135]
	s_barrier
	ds_read_b128 v[180:183], v153 offset:16384
	ds_read_b128 v[186:189], v153 offset:17408
	ds_read_b128 v[190:193], v153 offset:18432
	ds_read_b128 v[194:197], v153 offset:19456
	ds_read_b128 v[198:201], v153 offset:20480
	ds_read_b128 v[202:205], v153 offset:21504
	ds_read_b128 v[206:209], v153 offset:22528
	ds_read_b128 v[210:213], v153 offset:23552
	global_load_lds_dwordx4 v[234:235], off
	v_lshl_add_u64 v[236:237], s[48:49], 0, v[130:131]
	s_mov_b32 m0, s51
	s_nop 0
	global_load_lds_dwordx4 v[236:237], off
	s_barrier
	s_waitcnt lgkmcnt(0)
	v_mfma_f32_16x16x32_bf16 v[60:63], v[160:163], v[180:183], v[60:63]
	v_mfma_f32_16x16x32_bf16 v[60:63], v[164:167], v[186:189], v[60:63]
	v_mfma_f32_16x16x32_bf16 v[56:59], v[168:171], v[180:183], v[56:59]
	v_mfma_f32_16x16x32_bf16 v[56:59], v[176:179], v[186:189], v[56:59]
	v_mfma_f32_16x16x32_bf16 v[48:51], v[160:163], v[190:193], v[48:51]
	v_mfma_f32_16x16x32_bf16 v[48:51], v[164:167], v[194:197], v[48:51]
	v_mfma_f32_16x16x32_bf16 v[40:43], v[168:171], v[190:193], v[40:43]
	v_mfma_f32_16x16x32_bf16 v[40:43], v[176:179], v[194:197], v[40:43]
	v_mfma_f32_16x16x32_bf16 v[32:35], v[160:163], v[198:201], v[32:35]
	v_mfma_f32_16x16x32_bf16 v[32:35], v[164:167], v[202:205], v[32:35]
	v_mfma_f32_16x16x32_bf16 v[24:27], v[168:171], v[198:201], v[24:27]
	v_mfma_f32_16x16x32_bf16 v[24:27], v[176:179], v[202:205], v[24:27]
	v_mfma_f32_16x16x32_bf16 v[16:19], v[160:163], v[206:209], v[16:19]
	v_mfma_f32_16x16x32_bf16 v[16:19], v[164:167], v[210:213], v[16:19]
	v_mfma_f32_16x16x32_bf16 v[8:11], v[168:171], v[206:209], v[8:11]
	v_mfma_f32_16x16x32_bf16 v[8:11], v[176:179], v[210:213], v[8:11]
	s_barrier
	s_add_u32 s42, s46, 0x40000
	s_addc_u32 s43, s47, 0
	s_add_i32 s84, s77, s5
	v_lshl_add_u64 v[160:161], s[42:43], 0, v[132:133]
	s_mov_b32 m0, s84
	s_nop 0
	global_load_lds_dwordx4 v[160:161], off
	v_lshl_add_u64 v[160:161], s[42:43], 0, v[128:129]
	s_add_i32 m0, s84, 0x2000
	s_nop 0
	global_load_lds_dwordx4 v[160:161], off
	s_waitcnt vmcnt(6)
	s_barrier
	v_mfma_f32_16x16x32_bf16 v[52:55], v[214:217], v[180:183], v[52:55]
	v_mfma_f32_16x16x32_bf16 v[52:55], v[218:221], v[186:189], v[52:55]
	v_mfma_f32_16x16x32_bf16 v[44:47], v[222:225], v[180:183], v[44:47]
	v_mfma_f32_16x16x32_bf16 v[44:47], v[226:229], v[186:189], v[44:47]
	v_mfma_f32_16x16x32_bf16 v[36:39], v[214:217], v[190:193], v[36:39]
	v_mfma_f32_16x16x32_bf16 v[36:39], v[218:221], v[194:197], v[36:39]
	v_mfma_f32_16x16x32_bf16 v[28:31], v[222:225], v[190:193], v[28:31]
	v_mfma_f32_16x16x32_bf16 v[28:31], v[226:229], v[194:197], v[28:31]
	v_mfma_f32_16x16x32_bf16 v[20:23], v[214:217], v[198:201], v[20:23]
	v_mfma_f32_16x16x32_bf16 v[20:23], v[218:221], v[202:205], v[20:23]
	v_mfma_f32_16x16x32_bf16 v[12:15], v[222:225], v[198:201], v[12:15]
	v_mfma_f32_16x16x32_bf16 v[12:15], v[226:229], v[202:205], v[12:15]
	v_mfma_f32_16x16x32_bf16 v[4:7], v[214:217], v[206:209], v[4:7]
	v_mfma_f32_16x16x32_bf16 v[4:7], v[218:221], v[210:213], v[4:7]
	v_mfma_f32_16x16x32_bf16 v[0:3], v[222:225], v[206:209], v[0:3]
	v_mfma_f32_16x16x32_bf16 v[0:3], v[226:229], v[210:213], v[0:3]
	s_add_i32 s84, 0, 0x18000
	v_add_u32_e32 v157, s84, v139
	s_barrier
	ds_read_b128 v[160:163], v157
	ds_read_b128 v[164:167], v157 offset:1024
	ds_read_b128 v[168:171], v157 offset:2048
	ds_read_b128 v[176:179], v157 offset:3072
	s_add_u32 s42, s48, 0x170000
	s_addc_u32 s43, s49, 0
	s_mov_b32 m0, s52
	v_lshl_add_u64 v[214:215], s[42:43], 0, v[134:135]
	ds_read_b128 v[180:183], v153 offset:32768
	ds_read_b128 v[186:189], v153 offset:33792
	ds_read_b128 v[190:193], v153 offset:34816
	ds_read_b128 v[194:197], v153 offset:35840
	ds_read_b128 v[198:201], v153 offset:36864
	ds_read_b128 v[202:205], v153 offset:37888
	ds_read_b128 v[206:209], v153 offset:38912
	ds_read_b128 v[210:213], v153 offset:39936
	global_load_lds_dwordx4 v[214:215], off
	v_lshl_add_u64 v[214:215], s[42:43], 0, v[130:131]
	s_mov_b32 m0, s53
	s_nop 0
	global_load_lds_dwordx4 v[214:215], off
	s_waitcnt lgkmcnt(8)
	s_barrier
	s_waitcnt lgkmcnt(0)
	v_mfma_f32_16x16x32_bf16 v[124:127], v[160:163], v[180:183], v[124:127]
	v_mfma_f32_16x16x32_bf16 v[124:127], v[164:167], v[186:189], v[124:127]
	v_mfma_f32_16x16x32_bf16 v[120:123], v[168:171], v[180:183], v[120:123]
	v_mfma_f32_16x16x32_bf16 v[120:123], v[176:179], v[186:189], v[120:123]
	v_mfma_f32_16x16x32_bf16 v[112:115], v[160:163], v[190:193], v[112:115]
	v_mfma_f32_16x16x32_bf16 v[112:115], v[164:167], v[194:197], v[112:115]
	v_mfma_f32_16x16x32_bf16 v[104:107], v[168:171], v[190:193], v[104:107]
	v_mfma_f32_16x16x32_bf16 v[104:107], v[176:179], v[194:197], v[104:107]
	v_mfma_f32_16x16x32_bf16 v[96:99], v[160:163], v[198:201], v[96:99]
	v_mfma_f32_16x16x32_bf16 v[96:99], v[164:167], v[202:205], v[96:99]
	v_mfma_f32_16x16x32_bf16 v[88:91], v[168:171], v[198:201], v[88:91]
	v_mfma_f32_16x16x32_bf16 v[88:91], v[176:179], v[202:205], v[88:91]
	v_mfma_f32_16x16x32_bf16 v[80:83], v[160:163], v[206:209], v[80:83]
	v_mfma_f32_16x16x32_bf16 v[80:83], v[164:167], v[210:213], v[80:83]
	v_mfma_f32_16x16x32_bf16 v[72:75], v[168:171], v[206:209], v[72:75]
	v_mfma_f32_16x16x32_bf16 v[72:75], v[176:179], v[210:213], v[72:75]
	s_barrier
	s_add_i32 s48, 0, 0x1c000
	s_add_i32 s42, s84, s5
	v_add_u32_e32 v157, s48, v139
	v_lshl_add_u64 v[230:231], v[230:231], 0, s[10:11]
	s_mov_b32 m0, s42
	ds_read_b128 v[214:217], v157
	ds_read_b128 v[218:221], v157 offset:1024
	ds_read_b128 v[222:225], v157 offset:2048
	ds_read_b128 v[226:229], v157 offset:3072
	global_load_lds_dwordx4 v[230:231], off
	v_lshl_add_u64 v[230:231], v[232:233], 0, s[10:11]
	s_add_i32 m0, s42, 0x2000
	s_nop 0
	global_load_lds_dwordx4 v[230:231], off
	s_barrier
	s_waitcnt lgkmcnt(0)
	v_mfma_f32_16x16x32_bf16 v[116:119], v[214:217], v[180:183], v[116:119]
	v_mfma_f32_16x16x32_bf16 v[116:119], v[218:221], v[186:189], v[116:119]
	v_mfma_f32_16x16x32_bf16 v[108:111], v[222:225], v[180:183], v[108:111]
	v_mfma_f32_16x16x32_bf16 v[108:111], v[226:229], v[186:189], v[108:111]
	v_mfma_f32_16x16x32_bf16 v[100:103], v[214:217], v[190:193], v[100:103]
	v_mfma_f32_16x16x32_bf16 v[100:103], v[218:221], v[194:197], v[100:103]
	v_mfma_f32_16x16x32_bf16 v[92:95], v[222:225], v[190:193], v[92:95]
	v_mfma_f32_16x16x32_bf16 v[92:95], v[226:229], v[194:197], v[92:95]
	v_mfma_f32_16x16x32_bf16 v[84:87], v[214:217], v[198:201], v[84:87]
	v_mfma_f32_16x16x32_bf16 v[84:87], v[218:221], v[202:205], v[84:87]
	v_mfma_f32_16x16x32_bf16 v[76:79], v[222:225], v[198:201], v[76:79]
	v_mfma_f32_16x16x32_bf16 v[76:79], v[226:229], v[202:205], v[76:79]
	v_mfma_f32_16x16x32_bf16 v[68:71], v[214:217], v[206:209], v[68:71]
	v_mfma_f32_16x16x32_bf16 v[68:71], v[218:221], v[210:213], v[68:71]
	v_mfma_f32_16x16x32_bf16 v[64:67], v[222:225], v[206:209], v[64:67]
	v_mfma_f32_16x16x32_bf16 v[64:67], v[226:229], v[210:213], v[64:67]
	s_mov_b32 m0, s55
	v_lshl_add_u64 v[230:231], v[234:235], 0, s[10:11]
	s_barrier
	ds_read_b128 v[180:183], v153 offset:49152
	ds_read_b128 v[186:189], v153 offset:50176
	ds_read_b128 v[190:193], v153 offset:51200
	ds_read_b128 v[194:197], v153 offset:52224
	ds_read_b128 v[198:201], v153 offset:53248
	ds_read_b128 v[202:205], v153 offset:54272
	ds_read_b128 v[206:209], v153 offset:55296
	ds_read_b128 v[210:213], v153 offset:56320
	global_load_lds_dwordx4 v[230:231], off
	v_lshl_add_u64 v[230:231], v[236:237], 0, s[10:11]
	s_mov_b32 m0, s61
	s_nop 0
	global_load_lds_dwordx4 v[230:231], off
	s_barrier
	s_waitcnt lgkmcnt(0)
	v_mfma_f32_16x16x32_bf16 v[60:63], v[160:163], v[180:183], v[60:63]
	v_mfma_f32_16x16x32_bf16 v[60:63], v[164:167], v[186:189], v[60:63]
	v_mfma_f32_16x16x32_bf16 v[56:59], v[168:171], v[180:183], v[56:59]
	v_mfma_f32_16x16x32_bf16 v[56:59], v[176:179], v[186:189], v[56:59]
	v_mfma_f32_16x16x32_bf16 v[48:51], v[160:163], v[190:193], v[48:51]
	v_mfma_f32_16x16x32_bf16 v[48:51], v[164:167], v[194:197], v[48:51]
	v_mfma_f32_16x16x32_bf16 v[40:43], v[168:171], v[190:193], v[40:43]
	v_mfma_f32_16x16x32_bf16 v[40:43], v[176:179], v[194:197], v[40:43]
	v_mfma_f32_16x16x32_bf16 v[32:35], v[160:163], v[198:201], v[32:35]
	v_mfma_f32_16x16x32_bf16 v[32:35], v[164:167], v[202:205], v[32:35]
	v_mfma_f32_16x16x32_bf16 v[24:27], v[168:171], v[198:201], v[24:27]
	v_mfma_f32_16x16x32_bf16 v[24:27], v[176:179], v[202:205], v[24:27]
	v_mfma_f32_16x16x32_bf16 v[16:19], v[160:163], v[206:209], v[16:19]
	v_mfma_f32_16x16x32_bf16 v[16:19], v[164:167], v[210:213], v[16:19]
	v_mfma_f32_16x16x32_bf16 v[8:11], v[168:171], v[206:209], v[8:11]
	v_mfma_f32_16x16x32_bf16 v[8:11], v[176:179], v[210:213], v[8:11]
	s_barrier
	s_add_u32 s42, s46, 0x40080
	s_addc_u32 s43, s47, 0
	s_add_i32 s46, s48, s5
	v_lshl_add_u64 v[160:161], s[42:43], 0, v[132:133]
	s_mov_b32 m0, s46
	s_nop 0
	global_load_lds_dwordx4 v[160:161], off
	v_lshl_add_u64 v[160:161], s[42:43], 0, v[128:129]
	s_add_i32 m0, s46, 0x2000
	s_nop 0
	global_load_lds_dwordx4 v[160:161], off
	s_waitcnt vmcnt(6)
	s_barrier
	v_mfma_f32_16x16x32_bf16 v[52:55], v[214:217], v[180:183], v[52:55]
	v_mfma_f32_16x16x32_bf16 v[52:55], v[218:221], v[186:189], v[52:55]
	v_mfma_f32_16x16x32_bf16 v[44:47], v[222:225], v[180:183], v[44:47]
	v_mfma_f32_16x16x32_bf16 v[44:47], v[226:229], v[186:189], v[44:47]
	v_mfma_f32_16x16x32_bf16 v[36:39], v[214:217], v[190:193], v[36:39]
	v_mfma_f32_16x16x32_bf16 v[36:39], v[218:221], v[194:197], v[36:39]
	v_mfma_f32_16x16x32_bf16 v[28:31], v[222:225], v[190:193], v[28:31]
	v_mfma_f32_16x16x32_bf16 v[28:31], v[226:229], v[194:197], v[28:31]
	v_mfma_f32_16x16x32_bf16 v[20:23], v[214:217], v[198:201], v[20:23]
	v_mfma_f32_16x16x32_bf16 v[20:23], v[218:221], v[202:205], v[20:23]
	v_mfma_f32_16x16x32_bf16 v[12:15], v[222:225], v[198:201], v[12:15]
	v_mfma_f32_16x16x32_bf16 v[12:15], v[226:229], v[202:205], v[12:15]
	v_mfma_f32_16x16x32_bf16 v[4:7], v[214:217], v[206:209], v[4:7]
	v_mfma_f32_16x16x32_bf16 v[4:7], v[218:221], v[210:213], v[4:7]
	v_mfma_f32_16x16x32_bf16 v[0:3], v[222:225], v[206:209], v[0:3]
	v_mfma_f32_16x16x32_bf16 v[0:3], v[226:229], v[210:213], v[0:3]
	s_add_i32 s83, s83, 2
	s_add_u32 s63, s63, 0x100
	s_addc_u32 s82, s82, 0
	s_cmp_gt_u32 s83, 13
	s_mov_b64 s[42:43], s[44:45]
	s_barrier
	s_cbranch_scc0 .LBB0_301
	v_lshl_or_b32 v162, s81, 8, v141
	v_lshl_add_u32 v157, s80, 8, v137
	v_ashrrev_i32_e32 v163, 31, v162
	v_mov_b64_e32 v[160:161], s[12:13]
	v_mad_i64_i32 v[164:165], s[42:43], v157, s78, v[160:161]
	v_lshlrev_b64 v[162:163], 1, v[162:163]
	v_lshl_add_u64 v[164:165], v[164:165], 0, v[162:163]
	s_waitcnt vmcnt(0)
	v_pk_mul_f32 v[126:127], v[158:159], v[126:127] op_sel_hi:[0,1]
	v_pk_mul_f32 v[124:125], v[158:159], v[124:125] op_sel_hi:[0,1]
	v_pk_mul_f32 v[166:167], v[158:159], v[122:123] op_sel_hi:[0,1]
	v_pk_mul_f32 v[122:123], v[158:159], v[120:121] op_sel_hi:[0,1]
	v_cvt_pk_bf16_f32 v120, v124, v125
	v_cvt_pk_bf16_f32 v121, v126, v127
	v_cvt_pk_bf16_f32 v122, v122, v123
	v_cvt_pk_bf16_f32 v123, v166, v167
	global_store_dwordx4 v[164:165], v[120:123], off
	v_pk_mul_f32 v[116:117], v[158:159], v[116:117] op_sel_hi:[0,1]
	v_pk_mul_f32 v[118:119], v[158:159], v[118:119] op_sel_hi:[0,1]
	v_pk_mul_f32 v[120:121], v[158:159], v[110:111] op_sel_hi:[0,1]
	v_pk_mul_f32 v[110:111], v[158:159], v[108:109] op_sel_hi:[0,1]
	v_cvt_pk_bf16_f32 v108, v116, v117
	v_cvt_pk_bf16_f32 v109, v118, v119
	v_cvt_pk_bf16_f32 v110, v110, v111
	v_cvt_pk_bf16_f32 v111, v120, v121
	global_store_dwordx4 v[164:165], v[108:111], off offset:256
	v_pk_mul_f32 v[112:113], v[156:157], v[112:113] op_sel_hi:[0,1]
	v_pk_mul_f32 v[100:101], v[156:157], v[100:101] op_sel_hi:[0,1]
	v_or_b32_e32 v108, 16, v157
	v_mad_i64_i32 v[108:109], s[42:43], v108, s78, v[160:161]
	v_lshl_add_u64 v[108:109], v[108:109], 0, v[162:163]
	v_pk_mul_f32 v[110:111], v[156:157], v[114:115] op_sel_hi:[0,1]
	v_pk_mul_f32 v[114:115], v[156:157], v[106:107] op_sel_hi:[0,1]
	v_pk_mul_f32 v[106:107], v[156:157], v[104:105] op_sel_hi:[0,1]
	v_cvt_pk_bf16_f32 v104, v112, v113
	v_cvt_pk_bf16_f32 v105, v110, v111
	v_cvt_pk_bf16_f32 v106, v106, v107
	v_cvt_pk_bf16_f32 v107, v114, v115
	global_store_dwordx4 v[108:109], v[104:107], off
	v_pk_mul_f32 v[102:103], v[156:157], v[102:103] op_sel_hi:[0,1]
	v_pk_mul_f32 v[96:97], v[154:155], v[96:97] op_sel_hi:[0,1]
	v_pk_mul_f32 v[104:105], v[156:157], v[94:95] op_sel_hi:[0,1]
	v_pk_mul_f32 v[94:95], v[156:157], v[92:93] op_sel_hi:[0,1]
	v_cvt_pk_bf16_f32 v92, v100, v101
	v_cvt_pk_bf16_f32 v93, v102, v103
	v_cvt_pk_bf16_f32 v94, v94, v95
	v_cvt_pk_bf16_f32 v95, v104, v105
	global_store_dwordx4 v[108:109], v[92:95], off offset:256
	v_pk_mul_f32 v[84:85], v[154:155], v[84:85] op_sel_hi:[0,1]
	v_pk_mul_f32 v[86:87], v[154:155], v[86:87] op_sel_hi:[0,1]
	v_or_b32_e32 v92, 32, v157
	v_mad_i64_i32 v[92:93], s[42:43], v92, s78, v[160:161]
	v_lshl_add_u64 v[92:93], v[92:93], 0, v[162:163]
	v_pk_mul_f32 v[94:95], v[154:155], v[98:99] op_sel_hi:[0,1]
	v_pk_mul_f32 v[98:99], v[154:155], v[90:91] op_sel_hi:[0,1]
	v_pk_mul_f32 v[90:91], v[154:155], v[88:89] op_sel_hi:[0,1]
	v_cvt_pk_bf16_f32 v88, v96, v97
	v_cvt_pk_bf16_f32 v89, v94, v95
	v_cvt_pk_bf16_f32 v90, v90, v91
	v_cvt_pk_bf16_f32 v91, v98, v99
	global_store_dwordx4 v[92:93], v[88:91], off
	v_pk_mul_f32 v[80:81], v[152:153], v[80:81] op_sel_hi:[0,1]
	v_pk_mul_f32 v[68:69], v[152:153], v[68:69] op_sel_hi:[0,1]
	v_pk_mul_f32 v[88:89], v[154:155], v[78:79] op_sel_hi:[0,1]
	v_pk_mul_f32 v[78:79], v[154:155], v[76:77] op_sel_hi:[0,1]
	v_cvt_pk_bf16_f32 v76, v84, v85
	v_cvt_pk_bf16_f32 v77, v86, v87
	v_cvt_pk_bf16_f32 v78, v78, v79
	v_cvt_pk_bf16_f32 v79, v88, v89
	global_store_dwordx4 v[92:93], v[76:79], off offset:256
	v_pk_mul_f32 v[70:71], v[152:153], v[70:71] op_sel_hi:[0,1]
	v_pk_mul_f32 v[62:63], v[150:151], v[62:63] op_sel_hi:[0,1]
	v_or_b32_e32 v76, 48, v157
	v_mad_i64_i32 v[76:77], s[42:43], v76, s78, v[160:161]
	v_lshl_add_u64 v[76:77], v[76:77], 0, v[162:163]
	v_pk_mul_f32 v[78:79], v[152:153], v[82:83] op_sel_hi:[0,1]
	v_pk_mul_f32 v[82:83], v[152:153], v[74:75] op_sel_hi:[0,1]
	v_pk_mul_f32 v[74:75], v[152:153], v[72:73] op_sel_hi:[0,1]
	v_cvt_pk_bf16_f32 v72, v80, v81
	v_cvt_pk_bf16_f32 v73, v78, v79
	v_cvt_pk_bf16_f32 v74, v74, v75
	v_cvt_pk_bf16_f32 v75, v82, v83
	global_store_dwordx4 v[76:77], v[72:75], off
	v_pk_mul_f32 v[60:61], v[150:151], v[60:61] op_sel_hi:[0,1]
	v_pk_mul_f32 v[52:53], v[150:151], v[52:53] op_sel_hi:[0,1]
	v_pk_mul_f32 v[72:73], v[152:153], v[66:67] op_sel_hi:[0,1]
	v_pk_mul_f32 v[66:67], v[152:153], v[64:65] op_sel_hi:[0,1]
	v_cvt_pk_bf16_f32 v64, v68, v69
	v_cvt_pk_bf16_f32 v65, v70, v71
	v_cvt_pk_bf16_f32 v66, v66, v67
	v_cvt_pk_bf16_f32 v67, v72, v73
	global_store_dwordx4 v[76:77], v[64:67], off offset:256
	v_pk_mul_f32 v[54:55], v[150:151], v[54:55] op_sel_hi:[0,1]
	v_pk_mul_f32 v[48:49], v[140:141], v[48:49] op_sel_hi:[0,1]
	v_add_u32_e32 v64, 0x80, v157
	v_mad_i64_i32 v[64:65], s[42:43], v64, s78, v[160:161]
	v_lshl_add_u64 v[64:65], v[64:65], 0, v[162:163]
	v_pk_mul_f32 v[66:67], v[150:151], v[58:59] op_sel_hi:[0,1]
	v_pk_mul_f32 v[58:59], v[150:151], v[56:57] op_sel_hi:[0,1]
	v_cvt_pk_bf16_f32 v56, v60, v61
	v_cvt_pk_bf16_f32 v57, v62, v63
	v_cvt_pk_bf16_f32 v58, v58, v59
	v_cvt_pk_bf16_f32 v59, v66, v67
	global_store_dwordx4 v[64:65], v[56:59], off
	v_pk_mul_f32 v[36:37], v[140:141], v[36:37] op_sel_hi:[0,1]
	v_pk_mul_f32 v[38:39], v[140:141], v[38:39] op_sel_hi:[0,1]
	v_pk_mul_f32 v[56:57], v[150:151], v[46:47] op_sel_hi:[0,1]
	v_pk_mul_f32 v[46:47], v[150:151], v[44:45] op_sel_hi:[0,1]
	v_cvt_pk_bf16_f32 v44, v52, v53
	v_cvt_pk_bf16_f32 v45, v54, v55
	v_cvt_pk_bf16_f32 v46, v46, v47
	v_cvt_pk_bf16_f32 v47, v56, v57
	global_store_dwordx4 v[64:65], v[44:47], off offset:256
	v_pk_mul_f32 v[32:33], v[138:139], v[32:33] op_sel_hi:[0,1]
	v_pk_mul_f32 v[20:21], v[138:139], v[20:21] op_sel_hi:[0,1]
	v_add_u32_e32 v44, 0x90, v157
	v_mad_i64_i32 v[44:45], s[42:43], v44, s78, v[160:161]
	v_lshl_add_u64 v[44:45], v[44:45], 0, v[162:163]
	v_pk_mul_f32 v[46:47], v[140:141], v[50:51] op_sel_hi:[0,1]
	v_pk_mul_f32 v[50:51], v[140:141], v[42:43] op_sel_hi:[0,1]
	v_pk_mul_f32 v[42:43], v[140:141], v[40:41] op_sel_hi:[0,1]
	v_cvt_pk_bf16_f32 v40, v48, v49
	v_cvt_pk_bf16_f32 v41, v46, v47
	v_cvt_pk_bf16_f32 v42, v42, v43
	v_cvt_pk_bf16_f32 v43, v50, v51
	global_store_dwordx4 v[44:45], v[40:43], off
	v_pk_mul_f32 v[22:23], v[138:139], v[22:23] op_sel_hi:[0,1]
	v_pk_mul_f32 v[16:17], v[136:137], v[16:17] op_sel_hi:[0,1]
	v_pk_mul_f32 v[40:41], v[140:141], v[30:31] op_sel_hi:[0,1]
	v_pk_mul_f32 v[30:31], v[140:141], v[28:29] op_sel_hi:[0,1]
	v_cvt_pk_bf16_f32 v28, v36, v37
	v_cvt_pk_bf16_f32 v29, v38, v39
	v_cvt_pk_bf16_f32 v30, v30, v31
	v_cvt_pk_bf16_f32 v31, v40, v41
	global_store_dwordx4 v[44:45], v[28:31], off offset:256
	s_and_b64 vcc, s[8:9], exec
	v_pk_mul_f32 v[6:7], v[136:137], v[6:7] op_sel_hi:[0,1]
	v_add_u32_e32 v28, 0xa0, v157
	v_mad_i64_i32 v[28:29], s[42:43], v28, s78, v[160:161]
	v_lshl_add_u64 v[28:29], v[28:29], 0, v[162:163]
	v_pk_mul_f32 v[30:31], v[138:139], v[34:35] op_sel_hi:[0,1]
	v_pk_mul_f32 v[34:35], v[138:139], v[26:27] op_sel_hi:[0,1]
	v_pk_mul_f32 v[26:27], v[138:139], v[24:25] op_sel_hi:[0,1]
	v_cvt_pk_bf16_f32 v24, v32, v33
	v_cvt_pk_bf16_f32 v25, v30, v31
	v_cvt_pk_bf16_f32 v26, v26, v27
	v_cvt_pk_bf16_f32 v27, v34, v35
	global_store_dwordx4 v[28:29], v[24:27], off
	v_pk_mul_f32 v[4:5], v[136:137], v[4:5] op_sel_hi:[0,1]
	s_nop 0
	v_pk_mul_f32 v[24:25], v[138:139], v[14:15] op_sel_hi:[0,1]
	v_pk_mul_f32 v[14:15], v[138:139], v[12:13] op_sel_hi:[0,1]
	v_cvt_pk_bf16_f32 v12, v20, v21
	v_cvt_pk_bf16_f32 v13, v22, v23
	v_cvt_pk_bf16_f32 v14, v14, v15
	v_cvt_pk_bf16_f32 v15, v24, v25
	global_store_dwordx4 v[28:29], v[12:15], off offset:256
	s_nop 1
	v_add_u32_e32 v12, 0xb0, v157
	v_mad_i64_i32 v[12:13], s[42:43], v12, s78, v[160:161]
	v_lshl_add_u64 v[12:13], v[12:13], 0, v[162:163]
	v_pk_mul_f32 v[14:15], v[136:137], v[18:19] op_sel_hi:[0,1]
	v_pk_mul_f32 v[18:19], v[136:137], v[10:11] op_sel_hi:[0,1]
	v_pk_mul_f32 v[10:11], v[136:137], v[8:9] op_sel_hi:[0,1]
	v_cvt_pk_bf16_f32 v8, v16, v17
	v_cvt_pk_bf16_f32 v9, v14, v15
	v_cvt_pk_bf16_f32 v10, v10, v11
	v_cvt_pk_bf16_f32 v11, v18, v19
	global_store_dwordx4 v[12:13], v[8:11], off
	s_mov_b64 s[42:43], -1
	s_nop 0
	v_pk_mul_f32 v[8:9], v[136:137], v[2:3] op_sel_hi:[0,1]
	v_pk_mul_f32 v[2:3], v[136:137], v[0:1] op_sel_hi:[0,1]
	v_cvt_pk_bf16_f32 v0, v4, v5
	v_cvt_pk_bf16_f32 v1, v6, v7
	v_cvt_pk_bf16_f32 v2, v2, v3
	v_cvt_pk_bf16_f32 v3, v8, v9
	global_store_dwordx4 v[12:13], v[0:3], off offset:256
	s_cbranch_vccz .LBB0_295
	s_nop 0
	v_lshl_add_u32 v0, s79, 8, v137
	v_ashrrev_i32_e32 v1, 31, v0
	v_lshl_add_u64 v[0:1], v[0:1], 2, s[72:73]
	global_load_dword v158, v[0:1], off
	global_load_dword v156, v[0:1], off offset:64
	global_load_dword v154, v[0:1], off offset:128
	global_load_dword v152, v[0:1], off offset:192
	global_load_dword v150, v[0:1], off offset:512
	global_load_dword v140, v[0:1], off offset:576
	global_load_dword v138, v[0:1], off offset:640
	global_load_dword v136, v[0:1], off offset:704
	s_mov_b64 s[42:43], 0
	s_branch .LBB0_295

.LBB0_325:
	ds_read_b128 v[160:163], v151
	ds_read_b128 v[164:167], v151 offset:1024
	ds_read_b128 v[168:171], v151 offset:2048
	ds_read_b128 v[176:179], v151 offset:3072
	s_add_u32 s48, s46, 0x100
	s_addc_u32 s49, s47, 0
	s_cmp_eq_u32 s91, 4
	s_cselect_b32 s53, s43, s49
	s_cselect_b32 s52, s42, s48
	s_cselect_b32 s51, s41, s90
	s_cselect_b32 s50, s62, s63
	v_lshl_add_u64 v[214:215], s[46:47], 0, v[142:143]
	s_add_i32 m0, s55, 0xc000
	ds_read_b128 v[180:183], v153
	ds_read_b128 v[186:189], v153 offset:1024
	ds_read_b128 v[190:193], v153 offset:2048
	ds_read_b128 v[194:197], v153 offset:3072
	ds_read_b128 v[198:201], v153 offset:4096
	ds_read_b128 v[202:205], v153 offset:5120
	ds_read_b128 v[206:209], v153 offset:6144
	ds_read_b128 v[210:213], v153 offset:7168
	global_load_lds_dwordx4 v[214:215], off
	v_lshl_add_u64 v[214:215], s[46:47], 0, v[144:145]
	s_add_i32 m0, s55, 0xe000
	s_nop 0
	global_load_lds_dwordx4 v[214:215], off
	s_waitcnt lgkmcnt(8)
	s_barrier
	s_waitcnt lgkmcnt(0)
	v_mfma_f32_16x16x32_bf16 v[124:127], v[160:163], v[180:183], v[124:127]
	v_mfma_f32_16x16x32_bf16 v[124:127], v[164:167], v[186:189], v[124:127]
	v_mfma_f32_16x16x32_bf16 v[120:123], v[168:171], v[180:183], v[120:123]
	v_mfma_f32_16x16x32_bf16 v[120:123], v[176:179], v[186:189], v[120:123]
	v_mfma_f32_16x16x32_bf16 v[108:111], v[160:163], v[190:193], v[108:111]
	v_mfma_f32_16x16x32_bf16 v[108:111], v[164:167], v[194:197], v[108:111]
	v_mfma_f32_16x16x32_bf16 v[104:107], v[168:171], v[190:193], v[104:107]
	v_mfma_f32_16x16x32_bf16 v[104:107], v[176:179], v[194:197], v[104:107]
	v_mfma_f32_16x16x32_bf16 v[92:95], v[160:163], v[198:201], v[92:95]
	v_mfma_f32_16x16x32_bf16 v[92:95], v[164:167], v[202:205], v[92:95]
	v_mfma_f32_16x16x32_bf16 v[88:91], v[168:171], v[198:201], v[88:91]
	v_mfma_f32_16x16x32_bf16 v[88:91], v[176:179], v[202:205], v[88:91]
	v_mfma_f32_16x16x32_bf16 v[76:79], v[160:163], v[206:209], v[76:79]
	v_mfma_f32_16x16x32_bf16 v[76:79], v[164:167], v[210:213], v[76:79]
	v_mfma_f32_16x16x32_bf16 v[72:75], v[168:171], v[206:209], v[72:75]
	v_mfma_f32_16x16x32_bf16 v[72:75], v[176:179], v[210:213], v[72:75]
	s_barrier
	s_add_i32 s46, s81, s54
	v_lshl_add_u64 v[230:231], s[50:51], 0, v[130:131]
	s_mov_b32 m0, s46
	ds_read_b128 v[214:217], v155
	ds_read_b128 v[218:221], v155 offset:1024
	ds_read_b128 v[222:225], v155 offset:2048
	ds_read_b128 v[226:229], v155 offset:3072
	global_load_lds_dwordx4 v[230:231], off
	v_lshl_add_u64 v[232:233], s[50:51], 0, v[134:135]
	s_add_i32 m0, s46, 0x2000
	s_nop 0
	global_load_lds_dwordx4 v[232:233], off
	s_barrier
	s_waitcnt lgkmcnt(0)
	v_mfma_f32_16x16x32_bf16 v[116:119], v[214:217], v[180:183], v[116:119]
	v_mfma_f32_16x16x32_bf16 v[116:119], v[218:221], v[186:189], v[116:119]
	v_mfma_f32_16x16x32_bf16 v[112:115], v[222:225], v[180:183], v[112:115]
	v_mfma_f32_16x16x32_bf16 v[112:115], v[226:229], v[186:189], v[112:115]
	v_mfma_f32_16x16x32_bf16 v[100:103], v[214:217], v[190:193], v[100:103]
	v_mfma_f32_16x16x32_bf16 v[100:103], v[218:221], v[194:197], v[100:103]
	v_mfma_f32_16x16x32_bf16 v[96:99], v[222:225], v[190:193], v[96:99]
	v_mfma_f32_16x16x32_bf16 v[96:99], v[226:229], v[194:197], v[96:99]
	v_mfma_f32_16x16x32_bf16 v[84:87], v[214:217], v[198:201], v[84:87]
	v_mfma_f32_16x16x32_bf16 v[84:87], v[218:221], v[202:205], v[84:87]
	v_mfma_f32_16x16x32_bf16 v[80:83], v[222:225], v[198:201], v[80:83]
	v_mfma_f32_16x16x32_bf16 v[80:83], v[226:229], v[202:205], v[80:83]
	v_mfma_f32_16x16x32_bf16 v[68:71], v[214:217], v[206:209], v[68:71]
	v_mfma_f32_16x16x32_bf16 v[68:71], v[218:221], v[210:213], v[68:71]
	v_mfma_f32_16x16x32_bf16 v[64:67], v[222:225], v[206:209], v[64:67]
	v_mfma_f32_16x16x32_bf16 v[64:67], v[226:229], v[210:213], v[64:67]
	s_mov_b32 m0, s55
	v_lshl_add_u64 v[234:235], s[52:53], 0, v[128:129]
	s_barrier
	ds_read_b128 v[180:183], v153 offset:16384
	ds_read_b128 v[186:189], v153 offset:17408
	ds_read_b128 v[190:193], v153 offset:18432
	ds_read_b128 v[194:197], v153 offset:19456
	ds_read_b128 v[198:201], v153 offset:20480
	ds_read_b128 v[202:205], v153 offset:21504
	ds_read_b128 v[206:209], v153 offset:22528
	ds_read_b128 v[210:213], v153 offset:23552
	global_load_lds_dwordx4 v[234:235], off
	v_lshl_add_u64 v[236:237], s[52:53], 0, v[132:133]
	s_mov_b32 m0, s61
	s_nop 0
	global_load_lds_dwordx4 v[236:237], off
	s_barrier
	s_waitcnt lgkmcnt(0)
	v_mfma_f32_16x16x32_bf16 v[60:63], v[160:163], v[180:183], v[60:63]
	v_mfma_f32_16x16x32_bf16 v[60:63], v[164:167], v[186:189], v[60:63]
	v_mfma_f32_16x16x32_bf16 v[56:59], v[168:171], v[180:183], v[56:59]
	v_mfma_f32_16x16x32_bf16 v[56:59], v[176:179], v[186:189], v[56:59]
	v_mfma_f32_16x16x32_bf16 v[48:51], v[160:163], v[190:193], v[48:51]
	v_mfma_f32_16x16x32_bf16 v[48:51], v[164:167], v[194:197], v[48:51]
	v_mfma_f32_16x16x32_bf16 v[40:43], v[168:171], v[190:193], v[40:43]
	v_mfma_f32_16x16x32_bf16 v[40:43], v[176:179], v[194:197], v[40:43]
	v_mfma_f32_16x16x32_bf16 v[32:35], v[160:163], v[198:201], v[32:35]
	v_mfma_f32_16x16x32_bf16 v[32:35], v[164:167], v[202:205], v[32:35]
	v_mfma_f32_16x16x32_bf16 v[24:27], v[168:171], v[198:201], v[24:27]
	v_mfma_f32_16x16x32_bf16 v[24:27], v[176:179], v[202:205], v[24:27]
	v_mfma_f32_16x16x32_bf16 v[16:19], v[160:163], v[206:209], v[16:19]
	v_mfma_f32_16x16x32_bf16 v[16:19], v[164:167], v[210:213], v[16:19]
	v_mfma_f32_16x16x32_bf16 v[8:11], v[168:171], v[206:209], v[8:11]
	v_mfma_f32_16x16x32_bf16 v[8:11], v[176:179], v[210:213], v[8:11]
	s_barrier
	s_add_u32 s46, s50, 0x20000
	s_addc_u32 s47, s51, 0
	s_add_i32 s92, s82, s54
	v_lshl_add_u64 v[160:161], s[46:47], 0, v[130:131]
	s_mov_b32 m0, s92
	s_nop 0
	global_load_lds_dwordx4 v[160:161], off
	v_lshl_add_u64 v[160:161], s[46:47], 0, v[134:135]
	s_add_i32 m0, s92, 0x2000
	s_nop 0
	global_load_lds_dwordx4 v[160:161], off
	s_waitcnt vmcnt(6)
	s_barrier
	v_mfma_f32_16x16x32_bf16 v[52:55], v[214:217], v[180:183], v[52:55]
	v_mfma_f32_16x16x32_bf16 v[52:55], v[218:221], v[186:189], v[52:55]
	v_mfma_f32_16x16x32_bf16 v[44:47], v[222:225], v[180:183], v[44:47]
	v_mfma_f32_16x16x32_bf16 v[44:47], v[226:229], v[186:189], v[44:47]
	v_mfma_f32_16x16x32_bf16 v[36:39], v[214:217], v[190:193], v[36:39]
	v_mfma_f32_16x16x32_bf16 v[36:39], v[218:221], v[194:197], v[36:39]
	v_mfma_f32_16x16x32_bf16 v[28:31], v[222:225], v[190:193], v[28:31]
	v_mfma_f32_16x16x32_bf16 v[28:31], v[226:229], v[194:197], v[28:31]
	v_mfma_f32_16x16x32_bf16 v[20:23], v[214:217], v[198:201], v[20:23]
	v_mfma_f32_16x16x32_bf16 v[20:23], v[218:221], v[202:205], v[20:23]
	v_mfma_f32_16x16x32_bf16 v[12:15], v[222:225], v[198:201], v[12:15]
	v_mfma_f32_16x16x32_bf16 v[12:15], v[226:229], v[202:205], v[12:15]
	v_mfma_f32_16x16x32_bf16 v[4:7], v[214:217], v[206:209], v[4:7]
	v_mfma_f32_16x16x32_bf16 v[4:7], v[218:221], v[210:213], v[4:7]
	v_mfma_f32_16x16x32_bf16 v[0:3], v[222:225], v[206:209], v[0:3]
	v_mfma_f32_16x16x32_bf16 v[0:3], v[226:229], v[210:213], v[0:3]
	s_add_i32 s92, 0, 0x18000
	v_add_u32_e32 v157, s92, v139
	s_barrier
	ds_read_b128 v[160:163], v157
	ds_read_b128 v[164:167], v157 offset:1024
	ds_read_b128 v[168:171], v157 offset:2048
	ds_read_b128 v[176:179], v157 offset:3072
	s_add_u32 s46, s52, 0x170000
	s_addc_u32 s47, s53, 0
	s_mov_b32 m0, s74
	v_lshl_add_u64 v[214:215], s[46:47], 0, v[128:129]
	ds_read_b128 v[180:183], v153 offset:32768
	ds_read_b128 v[186:189], v153 offset:33792
	ds_read_b128 v[190:193], v153 offset:34816
	ds_read_b128 v[194:197], v153 offset:35840
	ds_read_b128 v[198:201], v153 offset:36864
	ds_read_b128 v[202:205], v153 offset:37888
	ds_read_b128 v[206:209], v153 offset:38912
	ds_read_b128 v[210:213], v153 offset:39936
	global_load_lds_dwordx4 v[214:215], off
	v_lshl_add_u64 v[214:215], s[46:47], 0, v[132:133]
	s_mov_b32 m0, s75
	s_nop 0
	global_load_lds_dwordx4 v[214:215], off
	s_waitcnt lgkmcnt(8)
	s_barrier
	s_waitcnt lgkmcnt(0)
	v_mfma_f32_16x16x32_bf16 v[124:127], v[160:163], v[180:183], v[124:127]
	v_mfma_f32_16x16x32_bf16 v[124:127], v[164:167], v[186:189], v[124:127]
	v_mfma_f32_16x16x32_bf16 v[120:123], v[168:171], v[180:183], v[120:123]
	v_mfma_f32_16x16x32_bf16 v[120:123], v[176:179], v[186:189], v[120:123]
	v_mfma_f32_16x16x32_bf16 v[108:111], v[160:163], v[190:193], v[108:111]
	v_mfma_f32_16x16x32_bf16 v[108:111], v[164:167], v[194:197], v[108:111]
	v_mfma_f32_16x16x32_bf16 v[104:107], v[168:171], v[190:193], v[104:107]
	v_mfma_f32_16x16x32_bf16 v[104:107], v[176:179], v[194:197], v[104:107]
	v_mfma_f32_16x16x32_bf16 v[92:95], v[160:163], v[198:201], v[92:95]
	v_mfma_f32_16x16x32_bf16 v[92:95], v[164:167], v[202:205], v[92:95]
	v_mfma_f32_16x16x32_bf16 v[88:91], v[168:171], v[198:201], v[88:91]
	v_mfma_f32_16x16x32_bf16 v[88:91], v[176:179], v[202:205], v[88:91]
	v_mfma_f32_16x16x32_bf16 v[76:79], v[160:163], v[206:209], v[76:79]
	v_mfma_f32_16x16x32_bf16 v[76:79], v[164:167], v[210:213], v[76:79]
	v_mfma_f32_16x16x32_bf16 v[72:75], v[168:171], v[206:209], v[72:75]
	v_mfma_f32_16x16x32_bf16 v[72:75], v[176:179], v[210:213], v[72:75]
	s_barrier
	s_add_i32 s52, 0, 0x1c000
	s_add_i32 s46, s92, s54
	v_add_u32_e32 v157, s52, v139
	v_lshl_add_u64 v[230:231], v[230:231], 0, s[10:11]
	s_mov_b32 m0, s46
	ds_read_b128 v[214:217], v157
	ds_read_b128 v[218:221], v157 offset:1024
	ds_read_b128 v[222:225], v157 offset:2048
	ds_read_b128 v[226:229], v157 offset:3072
	global_load_lds_dwordx4 v[230:231], off
	v_lshl_add_u64 v[230:231], v[232:233], 0, s[10:11]
	s_add_i32 m0, s46, 0x2000
	s_nop 0
	global_load_lds_dwordx4 v[230:231], off
	s_barrier
	s_waitcnt lgkmcnt(0)
	v_mfma_f32_16x16x32_bf16 v[116:119], v[214:217], v[180:183], v[116:119]
	v_mfma_f32_16x16x32_bf16 v[116:119], v[218:221], v[186:189], v[116:119]
	v_mfma_f32_16x16x32_bf16 v[112:115], v[222:225], v[180:183], v[112:115]
	v_mfma_f32_16x16x32_bf16 v[112:115], v[226:229], v[186:189], v[112:115]
	v_mfma_f32_16x16x32_bf16 v[100:103], v[214:217], v[190:193], v[100:103]
	v_mfma_f32_16x16x32_bf16 v[100:103], v[218:221], v[194:197], v[100:103]
	v_mfma_f32_16x16x32_bf16 v[96:99], v[222:225], v[190:193], v[96:99]
	v_mfma_f32_16x16x32_bf16 v[96:99], v[226:229], v[194:197], v[96:99]
	v_mfma_f32_16x16x32_bf16 v[84:87], v[214:217], v[198:201], v[84:87]
	v_mfma_f32_16x16x32_bf16 v[84:87], v[218:221], v[202:205], v[84:87]
	v_mfma_f32_16x16x32_bf16 v[80:83], v[222:225], v[198:201], v[80:83]
	v_mfma_f32_16x16x32_bf16 v[80:83], v[226:229], v[202:205], v[80:83]
	v_mfma_f32_16x16x32_bf16 v[68:71], v[214:217], v[206:209], v[68:71]
	v_mfma_f32_16x16x32_bf16 v[68:71], v[218:221], v[210:213], v[68:71]
	v_mfma_f32_16x16x32_bf16 v[64:67], v[222:225], v[206:209], v[64:67]
	v_mfma_f32_16x16x32_bf16 v[64:67], v[226:229], v[210:213], v[64:67]
	s_mov_b32 m0, s77
	v_lshl_add_u64 v[230:231], v[234:235], 0, s[10:11]
	s_barrier
	ds_read_b128 v[180:183], v153 offset:49152
	ds_read_b128 v[186:189], v153 offset:50176
	ds_read_b128 v[190:193], v153 offset:51200
	ds_read_b128 v[194:197], v153 offset:52224
	ds_read_b128 v[198:201], v153 offset:53248
	ds_read_b128 v[202:205], v153 offset:54272
	ds_read_b128 v[206:209], v153 offset:55296
	ds_read_b128 v[210:213], v153 offset:56320
	global_load_lds_dwordx4 v[230:231], off
	v_lshl_add_u64 v[230:231], v[236:237], 0, s[10:11]
	s_mov_b32 m0, s78
	s_nop 0
	global_load_lds_dwordx4 v[230:231], off
	s_barrier
	s_waitcnt lgkmcnt(0)
	v_mfma_f32_16x16x32_bf16 v[60:63], v[160:163], v[180:183], v[60:63]
	v_mfma_f32_16x16x32_bf16 v[60:63], v[164:167], v[186:189], v[60:63]
	v_mfma_f32_16x16x32_bf16 v[56:59], v[168:171], v[180:183], v[56:59]
	v_mfma_f32_16x16x32_bf16 v[56:59], v[176:179], v[186:189], v[56:59]
	v_mfma_f32_16x16x32_bf16 v[48:51], v[160:163], v[190:193], v[48:51]
	v_mfma_f32_16x16x32_bf16 v[48:51], v[164:167], v[194:197], v[48:51]
	v_mfma_f32_16x16x32_bf16 v[40:43], v[168:171], v[190:193], v[40:43]
	v_mfma_f32_16x16x32_bf16 v[40:43], v[176:179], v[194:197], v[40:43]
	v_mfma_f32_16x16x32_bf16 v[32:35], v[160:163], v[198:201], v[32:35]
	v_mfma_f32_16x16x32_bf16 v[32:35], v[164:167], v[202:205], v[32:35]
	v_mfma_f32_16x16x32_bf16 v[24:27], v[168:171], v[198:201], v[24:27]
	v_mfma_f32_16x16x32_bf16 v[24:27], v[176:179], v[202:205], v[24:27]
	v_mfma_f32_16x16x32_bf16 v[16:19], v[160:163], v[206:209], v[16:19]
	v_mfma_f32_16x16x32_bf16 v[16:19], v[164:167], v[210:213], v[16:19]
	v_mfma_f32_16x16x32_bf16 v[8:11], v[168:171], v[206:209], v[8:11]
	v_mfma_f32_16x16x32_bf16 v[8:11], v[176:179], v[210:213], v[8:11]
	s_barrier
	s_add_u32 s46, s50, 0x20080
	s_addc_u32 s47, s51, 0
	s_add_i32 s50, s52, s54
	v_lshl_add_u64 v[160:161], s[46:47], 0, v[130:131]
	s_mov_b32 m0, s50
	s_nop 0
	global_load_lds_dwordx4 v[160:161], off
	v_lshl_add_u64 v[160:161], s[46:47], 0, v[134:135]
	s_add_i32 m0, s50, 0x2000
	s_nop 0
	global_load_lds_dwordx4 v[160:161], off
	s_waitcnt vmcnt(6)
	s_barrier
	v_mfma_f32_16x16x32_bf16 v[52:55], v[214:217], v[180:183], v[52:55]
	v_mfma_f32_16x16x32_bf16 v[52:55], v[218:221], v[186:189], v[52:55]
	v_mfma_f32_16x16x32_bf16 v[44:47], v[222:225], v[180:183], v[44:47]
	v_mfma_f32_16x16x32_bf16 v[44:47], v[226:229], v[186:189], v[44:47]
	v_mfma_f32_16x16x32_bf16 v[36:39], v[214:217], v[190:193], v[36:39]
	v_mfma_f32_16x16x32_bf16 v[36:39], v[218:221], v[194:197], v[36:39]
	v_mfma_f32_16x16x32_bf16 v[28:31], v[222:225], v[190:193], v[28:31]
	v_mfma_f32_16x16x32_bf16 v[28:31], v[226:229], v[194:197], v[28:31]
	v_mfma_f32_16x16x32_bf16 v[20:23], v[214:217], v[198:201], v[20:23]
	v_mfma_f32_16x16x32_bf16 v[20:23], v[218:221], v[202:205], v[20:23]
	v_mfma_f32_16x16x32_bf16 v[12:15], v[222:225], v[198:201], v[12:15]
	v_mfma_f32_16x16x32_bf16 v[12:15], v[226:229], v[202:205], v[12:15]
	v_mfma_f32_16x16x32_bf16 v[4:7], v[214:217], v[206:209], v[4:7]
	v_mfma_f32_16x16x32_bf16 v[4:7], v[218:221], v[210:213], v[4:7]
	v_mfma_f32_16x16x32_bf16 v[0:3], v[222:225], v[206:209], v[0:3]
	v_mfma_f32_16x16x32_bf16 v[0:3], v[226:229], v[210:213], v[0:3]
	s_add_i32 s91, s91, 2
	s_add_u32 s63, s63, 0x100
	s_addc_u32 s90, s90, 0
	s_cmp_gt_u32 s91, 5
	s_mov_b64 s[46:47], s[48:49]
	s_barrier
	s_cbranch_scc0 .LBB0_325
	v_lshl_add_u32 v162, s88, 8, v137
	v_lshl_or_b32 v160, s89, 8, v141
	v_ashrrev_i32_e32 v163, 31, v162
	v_ashrrev_i32_e32 v161, 31, v160
	v_lshlrev_b64 v[164:165], 14, v[162:163]
	v_lshl_add_u64 v[164:165], s[56:57], 0, v[164:165]
	v_lshlrev_b64 v[166:167], 1, v[160:161]
	v_lshl_add_u64 v[160:161], v[164:165], 0, v[166:167]
	s_waitcnt vmcnt(0)
	v_pk_mul_f32 v[126:127], v[158:159], v[126:127] op_sel_hi:[0,1]
	v_pk_mul_f32 v[124:125], v[158:159], v[124:125] op_sel_hi:[0,1]
	v_pk_mul_f32 v[164:165], v[158:159], v[122:123] op_sel_hi:[0,1]
	v_pk_mul_f32 v[122:123], v[158:159], v[120:121] op_sel_hi:[0,1]
	v_cvt_pk_bf16_f32 v120, v124, v125
	v_cvt_pk_bf16_f32 v121, v126, v127
	v_cvt_pk_bf16_f32 v122, v122, v123
	v_cvt_pk_bf16_f32 v123, v164, v165
	global_store_dwordx4 v[160:161], v[120:123], off
	v_pk_mul_f32 v[116:117], v[158:159], v[116:117] op_sel_hi:[0,1]
	v_pk_mul_f32 v[118:119], v[158:159], v[118:119] op_sel_hi:[0,1]
	v_pk_mul_f32 v[120:121], v[158:159], v[114:115] op_sel_hi:[0,1]
	v_pk_mul_f32 v[114:115], v[158:159], v[112:113] op_sel_hi:[0,1]
	v_cvt_pk_bf16_f32 v112, v116, v117
	v_cvt_pk_bf16_f32 v113, v118, v119
	v_cvt_pk_bf16_f32 v114, v114, v115
	v_cvt_pk_bf16_f32 v115, v120, v121
	global_store_dwordx4 v[160:161], v[112:115], off offset:256
	v_pk_mul_f32 v[110:111], v[156:157], v[110:111] op_sel_hi:[0,1]
	v_pk_mul_f32 v[108:109], v[156:157], v[108:109] op_sel_hi:[0,1]
	v_or_b32_e32 v112, 16, v162
	v_ashrrev_i32_e32 v113, 31, v112
	v_lshlrev_b64 v[112:113], 14, v[112:113]
	v_lshl_add_u64 v[112:113], s[56:57], 0, v[112:113]
	v_lshl_add_u64 v[112:113], v[112:113], 0, v[166:167]
	v_pk_mul_f32 v[114:115], v[156:157], v[106:107] op_sel_hi:[0,1]
	v_pk_mul_f32 v[106:107], v[156:157], v[104:105] op_sel_hi:[0,1]
	v_cvt_pk_bf16_f32 v104, v108, v109
	v_cvt_pk_bf16_f32 v105, v110, v111
	v_cvt_pk_bf16_f32 v106, v106, v107
	v_cvt_pk_bf16_f32 v107, v114, v115
	global_store_dwordx4 v[112:113], v[104:107], off
	v_pk_mul_f32 v[100:101], v[156:157], v[100:101] op_sel_hi:[0,1]
	v_pk_mul_f32 v[102:103], v[156:157], v[102:103] op_sel_hi:[0,1]
	v_pk_mul_f32 v[104:105], v[156:157], v[98:99] op_sel_hi:[0,1]
	v_pk_mul_f32 v[98:99], v[156:157], v[96:97] op_sel_hi:[0,1]
	v_cvt_pk_bf16_f32 v96, v100, v101
	v_cvt_pk_bf16_f32 v97, v102, v103
	v_cvt_pk_bf16_f32 v98, v98, v99
	v_cvt_pk_bf16_f32 v99, v104, v105
	global_store_dwordx4 v[112:113], v[96:99], off offset:256
	v_pk_mul_f32 v[94:95], v[154:155], v[94:95] op_sel_hi:[0,1]
	v_pk_mul_f32 v[92:93], v[154:155], v[92:93] op_sel_hi:[0,1]
	v_or_b32_e32 v96, 32, v162
	v_ashrrev_i32_e32 v97, 31, v96
	v_lshlrev_b64 v[96:97], 14, v[96:97]
	v_lshl_add_u64 v[96:97], s[56:57], 0, v[96:97]
	v_lshl_add_u64 v[96:97], v[96:97], 0, v[166:167]
	v_pk_mul_f32 v[98:99], v[154:155], v[90:91] op_sel_hi:[0,1]
	v_pk_mul_f32 v[90:91], v[154:155], v[88:89] op_sel_hi:[0,1]
	v_cvt_pk_bf16_f32 v88, v92, v93
	v_cvt_pk_bf16_f32 v89, v94, v95
	v_cvt_pk_bf16_f32 v90, v90, v91
	v_cvt_pk_bf16_f32 v91, v98, v99
	global_store_dwordx4 v[96:97], v[88:91], off
	v_pk_mul_f32 v[84:85], v[154:155], v[84:85] op_sel_hi:[0,1]
	v_pk_mul_f32 v[86:87], v[154:155], v[86:87] op_sel_hi:[0,1]
	v_pk_mul_f32 v[88:89], v[154:155], v[82:83] op_sel_hi:[0,1]
	v_pk_mul_f32 v[82:83], v[154:155], v[80:81] op_sel_hi:[0,1]
	v_cvt_pk_bf16_f32 v80, v84, v85
	v_cvt_pk_bf16_f32 v81, v86, v87
	v_cvt_pk_bf16_f32 v82, v82, v83
	v_cvt_pk_bf16_f32 v83, v88, v89
	global_store_dwordx4 v[96:97], v[80:83], off offset:256
	v_pk_mul_f32 v[78:79], v[152:153], v[78:79] op_sel_hi:[0,1]
	v_pk_mul_f32 v[76:77], v[152:153], v[76:77] op_sel_hi:[0,1]
	v_or_b32_e32 v80, 48, v162
	v_ashrrev_i32_e32 v81, 31, v80
	v_lshlrev_b64 v[80:81], 14, v[80:81]
	v_lshl_add_u64 v[80:81], s[56:57], 0, v[80:81]
	v_lshl_add_u64 v[80:81], v[80:81], 0, v[166:167]
	v_pk_mul_f32 v[82:83], v[152:153], v[74:75] op_sel_hi:[0,1]
	v_pk_mul_f32 v[74:75], v[152:153], v[72:73] op_sel_hi:[0,1]
	v_cvt_pk_bf16_f32 v72, v76, v77
	v_cvt_pk_bf16_f32 v73, v78, v79
	v_cvt_pk_bf16_f32 v74, v74, v75
	v_cvt_pk_bf16_f32 v75, v82, v83
	global_store_dwordx4 v[80:81], v[72:75], off
	v_pk_mul_f32 v[70:71], v[152:153], v[70:71] op_sel_hi:[0,1]
	v_pk_mul_f32 v[68:69], v[152:153], v[68:69] op_sel_hi:[0,1]
	v_pk_mul_f32 v[72:73], v[152:153], v[66:67] op_sel_hi:[0,1]
	v_pk_mul_f32 v[66:67], v[152:153], v[64:65] op_sel_hi:[0,1]
	v_cvt_pk_bf16_f32 v64, v68, v69
	v_cvt_pk_bf16_f32 v65, v70, v71
	v_cvt_pk_bf16_f32 v66, v66, v67
	v_cvt_pk_bf16_f32 v67, v72, v73
	v_pk_mul_f32 v[60:61], v[150:151], v[60:61] op_sel_hi:[0,1]
	global_store_dwordx4 v[80:81], v[64:67], off offset:256
	v_pk_mul_f32 v[62:63], v[150:151], v[62:63] op_sel_hi:[0,1]
	s_mov_b64 s[46:47], 0x200000
	v_pk_mul_f32 v[66:67], v[150:151], v[58:59] op_sel_hi:[0,1]
	v_pk_mul_f32 v[58:59], v[150:151], v[56:57] op_sel_hi:[0,1]
	v_cvt_pk_bf16_f32 v56, v60, v61
	v_add_co_u32_e32 v60, vcc, s83, v160
	v_cvt_pk_bf16_f32 v57, v62, v63
	v_cvt_pk_bf16_f32 v58, v58, v59
	v_cvt_pk_bf16_f32 v59, v66, v67
	v_lshl_add_u64 v[64:65], v[160:161], 0, s[46:47]
	s_nop 0
	v_addc_co_u32_e32 v61, vcc, 0, v161, vcc
	global_store_dwordx4 v[60:61], v[56:59], off
	v_pk_mul_f32 v[54:55], v[150:151], v[54:55] op_sel_hi:[0,1]
	v_pk_mul_f32 v[52:53], v[150:151], v[52:53] op_sel_hi:[0,1]
	v_pk_mul_f32 v[56:57], v[150:151], v[46:47] op_sel_hi:[0,1]
	v_pk_mul_f32 v[46:47], v[150:151], v[44:45] op_sel_hi:[0,1]
	v_cvt_pk_bf16_f32 v44, v52, v53
	v_cvt_pk_bf16_f32 v45, v54, v55
	v_cvt_pk_bf16_f32 v46, v46, v47
	v_cvt_pk_bf16_f32 v47, v56, v57
	global_store_dwordx4 v[64:65], v[44:47], off offset:256
	v_pk_mul_f32 v[48:49], v[140:141], v[48:49] op_sel_hi:[0,1]
	v_pk_mul_f32 v[38:39], v[140:141], v[38:39] op_sel_hi:[0,1]
	v_pk_mul_f32 v[46:47], v[140:141], v[50:51] op_sel_hi:[0,1]
	v_pk_mul_f32 v[50:51], v[140:141], v[42:43] op_sel_hi:[0,1]
	v_pk_mul_f32 v[42:43], v[140:141], v[40:41] op_sel_hi:[0,1]
	v_cvt_pk_bf16_f32 v40, v48, v49
	v_cvt_pk_bf16_f32 v41, v46, v47
	v_add_co_u32_e32 v46, vcc, s84, v160
	v_cvt_pk_bf16_f32 v42, v42, v43
	v_cvt_pk_bf16_f32 v43, v50, v51
	v_lshl_add_u64 v[44:45], v[160:161], 0, s[30:31]
	s_nop 0
	v_addc_co_u32_e32 v47, vcc, 0, v161, vcc
	global_store_dwordx4 v[46:47], v[40:43], off
	v_pk_mul_f32 v[36:37], v[140:141], v[36:37] op_sel_hi:[0,1]
	v_pk_mul_f32 v[32:33], v[138:139], v[32:33] op_sel_hi:[0,1]
	v_pk_mul_f32 v[40:41], v[140:141], v[30:31] op_sel_hi:[0,1]
	v_pk_mul_f32 v[30:31], v[140:141], v[28:29] op_sel_hi:[0,1]
	v_cvt_pk_bf16_f32 v28, v36, v37
	v_cvt_pk_bf16_f32 v29, v38, v39
	v_cvt_pk_bf16_f32 v30, v30, v31
	v_cvt_pk_bf16_f32 v31, v40, v41
	global_store_dwordx4 v[44:45], v[28:31], off offset:256
	v_pk_mul_f32 v[22:23], v[138:139], v[22:23] op_sel_hi:[0,1]
	v_pk_mul_f32 v[20:21], v[138:139], v[20:21] op_sel_hi:[0,1]
	v_pk_mul_f32 v[30:31], v[138:139], v[34:35] op_sel_hi:[0,1]
	v_pk_mul_f32 v[34:35], v[138:139], v[26:27] op_sel_hi:[0,1]
	v_pk_mul_f32 v[26:27], v[138:139], v[24:25] op_sel_hi:[0,1]
	v_cvt_pk_bf16_f32 v24, v32, v33
	v_cvt_pk_bf16_f32 v25, v30, v31
	v_add_co_u32_e32 v30, vcc, s85, v160
	v_cvt_pk_bf16_f32 v26, v26, v27
	v_cvt_pk_bf16_f32 v27, v34, v35
	v_lshl_add_u64 v[28:29], v[160:161], 0, s[36:37]
	s_nop 0
	v_addc_co_u32_e32 v31, vcc, 0, v161, vcc
	global_store_dwordx4 v[30:31], v[24:27], off
	v_pk_mul_f32 v[16:17], v[136:137], v[16:17] op_sel_hi:[0,1]
	s_mov_b64 s[46:47], -1
	v_pk_mul_f32 v[24:25], v[138:139], v[14:15] op_sel_hi:[0,1]
	v_pk_mul_f32 v[14:15], v[138:139], v[12:13] op_sel_hi:[0,1]
	v_cvt_pk_bf16_f32 v12, v20, v21
	v_cvt_pk_bf16_f32 v13, v22, v23
	v_cvt_pk_bf16_f32 v14, v14, v15
	v_cvt_pk_bf16_f32 v15, v24, v25
	global_store_dwordx4 v[28:29], v[12:15], off offset:256
	v_pk_mul_f32 v[6:7], v[136:137], v[6:7] op_sel_hi:[0,1]
	v_pk_mul_f32 v[4:5], v[136:137], v[4:5] op_sel_hi:[0,1]
	v_pk_mul_f32 v[14:15], v[136:137], v[18:19] op_sel_hi:[0,1]
	v_pk_mul_f32 v[18:19], v[136:137], v[10:11] op_sel_hi:[0,1]
	v_pk_mul_f32 v[10:11], v[136:137], v[8:9] op_sel_hi:[0,1]
	v_cvt_pk_bf16_f32 v8, v16, v17
	v_cvt_pk_bf16_f32 v9, v14, v15
	v_add_co_u32_e32 v14, vcc, s86, v160
	v_lshl_add_u64 v[12:13], v[160:161], 0, s[38:39]
	s_nop 0
	v_addc_co_u32_e32 v15, vcc, 0, v161, vcc
	v_cvt_pk_bf16_f32 v10, v10, v11
	v_cvt_pk_bf16_f32 v11, v18, v19
	global_store_dwordx4 v[14:15], v[8:11], off
	s_and_b64 vcc, s[8:9], exec
	s_nop 0
	v_pk_mul_f32 v[8:9], v[136:137], v[2:3] op_sel_hi:[0,1]
	v_pk_mul_f32 v[2:3], v[136:137], v[0:1] op_sel_hi:[0,1]
	v_cvt_pk_bf16_f32 v0, v4, v5
	v_cvt_pk_bf16_f32 v1, v6, v7
	v_cvt_pk_bf16_f32 v2, v2, v3
	v_cvt_pk_bf16_f32 v3, v8, v9
	global_store_dwordx4 v[12:13], v[0:3], off offset:256
	s_cbranch_vccz .LBB0_315
	s_nop 0
	v_lshl_add_u32 v0, s87, 8, v137
	v_ashrrev_i32_e32 v1, 31, v0
	v_lshl_add_u64 v[0:1], v[0:1], 2, s[34:35]
	global_load_dword v158, v[0:1], off
	global_load_dword v156, v[0:1], off offset:64
	global_load_dword v154, v[0:1], off offset:128
	global_load_dword v152, v[0:1], off offset:192
	global_load_dword v150, v[0:1], off offset:512
	global_load_dword v140, v[0:1], off offset:576
	global_load_dword v138, v[0:1], off offset:640
	global_load_dword v136, v[0:1], off offset:704
	s_mov_b64 s[46:47], 0
	s_branch .LBB0_315

.LBB0_514:
	ds_read_b128 v[128:131], v171
	ds_read_b128 v[132:135], v171 offset:1024
	ds_read_b128 v[136:139], v171 offset:2048
	ds_read_b128 v[140:143], v171 offset:3072
	s_add_u32 s40, s38, 0xfff00080
	s_addc_u32 s41, s39, -1
	s_cmp_eq_u32 s61, 60
	s_cselect_b32 s43, s6, s41
	s_cselect_b32 s42, s7, s40
	s_cselect_b32 s41, s25, s55
	s_cselect_b32 s40, s27, s35
	v_lshl_add_u64 v[202:203], s[38:39], 0, v[152:153]
	s_add_i32 m0, s37, 0xc000
	ds_read_b128 v[160:163], v173
	ds_read_b128 v[164:167], v173 offset:1024
	ds_read_b128 v[176:179], v173 offset:2048
	ds_read_b128 v[180:183], v173 offset:3072
	ds_read_b128 v[186:189], v173 offset:4096
	ds_read_b128 v[190:193], v173 offset:5120
	ds_read_b128 v[194:197], v173 offset:6144
	ds_read_b128 v[198:201], v173 offset:7168
	global_load_lds_dwordx4 v[202:203], off
	v_lshl_add_u64 v[202:203], s[38:39], 0, v[154:155]
	s_add_i32 m0, s37, 0xe000
	s_nop 0
	global_load_lds_dwordx4 v[202:203], off
	s_waitcnt lgkmcnt(8)
	s_barrier
	s_waitcnt lgkmcnt(0)
	v_mfma_f32_16x16x32_bf16 v[124:127], v[128:131], v[160:163], v[124:127]
	v_mfma_f32_16x16x32_bf16 v[124:127], v[132:135], v[164:167], v[124:127]
	v_mfma_f32_16x16x32_bf16 v[120:123], v[136:139], v[160:163], v[120:123]
	v_mfma_f32_16x16x32_bf16 v[120:123], v[140:143], v[164:167], v[120:123]
	v_mfma_f32_16x16x32_bf16 v[108:111], v[128:131], v[176:179], v[108:111]
	v_mfma_f32_16x16x32_bf16 v[108:111], v[132:135], v[180:183], v[108:111]
	v_mfma_f32_16x16x32_bf16 v[104:107], v[136:139], v[176:179], v[104:107]
	v_mfma_f32_16x16x32_bf16 v[104:107], v[140:143], v[180:183], v[104:107]
	v_mfma_f32_16x16x32_bf16 v[92:95], v[128:131], v[186:189], v[92:95]
	v_mfma_f32_16x16x32_bf16 v[92:95], v[132:135], v[190:193], v[92:95]
	v_mfma_f32_16x16x32_bf16 v[88:91], v[136:139], v[186:189], v[88:91]
	v_mfma_f32_16x16x32_bf16 v[88:91], v[140:143], v[190:193], v[88:91]
	v_mfma_f32_16x16x32_bf16 v[76:79], v[128:131], v[194:197], v[76:79]
	v_mfma_f32_16x16x32_bf16 v[76:79], v[132:135], v[198:201], v[76:79]
	v_mfma_f32_16x16x32_bf16 v[72:75], v[136:139], v[194:197], v[72:75]
	v_mfma_f32_16x16x32_bf16 v[72:75], v[140:143], v[198:201], v[72:75]
	s_barrier
	s_add_i32 s62, s53, s5
	v_lshl_add_u64 v[218:219], s[40:41], 0, v[146:147]
	s_mov_b32 m0, s62
	ds_read_b128 v[202:205], v174
	ds_read_b128 v[206:209], v174 offset:1024
	ds_read_b128 v[210:213], v174 offset:2048
	ds_read_b128 v[214:217], v174 offset:3072
	global_load_lds_dwordx4 v[218:219], off
	v_lshl_add_u64 v[220:221], s[40:41], 0, v[150:151]
	s_add_i32 m0, s62, 0x2000
	s_nop 0
	global_load_lds_dwordx4 v[220:221], off
	s_barrier
	s_waitcnt lgkmcnt(0)
	v_mfma_f32_16x16x32_bf16 v[116:119], v[202:205], v[160:163], v[116:119]
	v_mfma_f32_16x16x32_bf16 v[116:119], v[206:209], v[164:167], v[116:119]
	v_mfma_f32_16x16x32_bf16 v[112:115], v[210:213], v[160:163], v[112:115]
	v_mfma_f32_16x16x32_bf16 v[112:115], v[214:217], v[164:167], v[112:115]
	v_mfma_f32_16x16x32_bf16 v[100:103], v[202:205], v[176:179], v[100:103]
	v_mfma_f32_16x16x32_bf16 v[100:103], v[206:209], v[180:183], v[100:103]
	v_mfma_f32_16x16x32_bf16 v[96:99], v[210:213], v[176:179], v[96:99]
	v_mfma_f32_16x16x32_bf16 v[96:99], v[214:217], v[180:183], v[96:99]
	v_mfma_f32_16x16x32_bf16 v[84:87], v[202:205], v[186:189], v[84:87]
	v_mfma_f32_16x16x32_bf16 v[84:87], v[206:209], v[190:193], v[84:87]
	v_mfma_f32_16x16x32_bf16 v[80:83], v[210:213], v[186:189], v[80:83]
	v_mfma_f32_16x16x32_bf16 v[80:83], v[214:217], v[190:193], v[80:83]
	v_mfma_f32_16x16x32_bf16 v[68:71], v[202:205], v[194:197], v[68:71]
	v_mfma_f32_16x16x32_bf16 v[68:71], v[206:209], v[198:201], v[68:71]
	v_mfma_f32_16x16x32_bf16 v[64:67], v[210:213], v[194:197], v[64:67]
	v_mfma_f32_16x16x32_bf16 v[64:67], v[214:217], v[198:201], v[64:67]
	s_mov_b32 m0, s37
	v_lshl_add_u64 v[222:223], s[42:43], 0, v[144:145]
	s_barrier
	ds_read_b128 v[160:163], v173 offset:16384
	ds_read_b128 v[164:167], v173 offset:17408
	ds_read_b128 v[176:179], v173 offset:18432
	ds_read_b128 v[180:183], v173 offset:19456
	ds_read_b128 v[186:189], v173 offset:20480
	ds_read_b128 v[190:193], v173 offset:21504
	ds_read_b128 v[194:197], v173 offset:22528
	ds_read_b128 v[198:201], v173 offset:23552
	global_load_lds_dwordx4 v[222:223], off
	v_lshl_add_u64 v[224:225], s[42:43], 0, v[148:149]
	s_mov_b32 m0, s44
	s_nop 0
	global_load_lds_dwordx4 v[224:225], off
	s_barrier
	s_waitcnt lgkmcnt(0)
	v_mfma_f32_16x16x32_bf16 v[60:63], v[128:131], v[160:163], v[60:63]
	v_mfma_f32_16x16x32_bf16 v[60:63], v[132:135], v[164:167], v[60:63]
	v_mfma_f32_16x16x32_bf16 v[56:59], v[136:139], v[160:163], v[56:59]
	v_mfma_f32_16x16x32_bf16 v[56:59], v[140:143], v[164:167], v[56:59]
	v_mfma_f32_16x16x32_bf16 v[44:47], v[128:131], v[176:179], v[44:47]
	v_mfma_f32_16x16x32_bf16 v[44:47], v[132:135], v[180:183], v[44:47]
	v_mfma_f32_16x16x32_bf16 v[40:43], v[136:139], v[176:179], v[40:43]
	v_mfma_f32_16x16x32_bf16 v[40:43], v[140:143], v[180:183], v[40:43]
	v_mfma_f32_16x16x32_bf16 v[28:31], v[128:131], v[186:189], v[28:31]
	v_mfma_f32_16x16x32_bf16 v[28:31], v[132:135], v[190:193], v[28:31]
	v_mfma_f32_16x16x32_bf16 v[24:27], v[136:139], v[186:189], v[24:27]
	v_mfma_f32_16x16x32_bf16 v[24:27], v[140:143], v[190:193], v[24:27]
	v_mfma_f32_16x16x32_bf16 v[12:15], v[128:131], v[194:197], v[12:15]
	v_mfma_f32_16x16x32_bf16 v[12:15], v[132:135], v[198:201], v[12:15]
	v_mfma_f32_16x16x32_bf16 v[8:11], v[136:139], v[194:197], v[8:11]
	v_mfma_f32_16x16x32_bf16 v[8:11], v[140:143], v[198:201], v[8:11]
	s_barrier
	s_add_u32 s62, s40, 0x100000
	s_addc_u32 s63, s41, 0
	s_add_i32 s74, s54, s5
	v_lshl_add_u64 v[128:129], s[62:63], 0, v[146:147]
	s_mov_b32 m0, s74
	s_nop 0
	global_load_lds_dwordx4 v[128:129], off
	v_lshl_add_u64 v[128:129], s[62:63], 0, v[150:151]
	s_add_i32 m0, s74, 0x2000
	s_nop 0
	global_load_lds_dwordx4 v[128:129], off
	s_waitcnt vmcnt(6)
	s_barrier
	v_mfma_f32_16x16x32_bf16 v[52:55], v[202:205], v[160:163], v[52:55]
	v_mfma_f32_16x16x32_bf16 v[52:55], v[206:209], v[164:167], v[52:55]
	v_mfma_f32_16x16x32_bf16 v[48:51], v[210:213], v[160:163], v[48:51]
	v_mfma_f32_16x16x32_bf16 v[48:51], v[214:217], v[164:167], v[48:51]
	v_mfma_f32_16x16x32_bf16 v[36:39], v[202:205], v[176:179], v[36:39]
	v_mfma_f32_16x16x32_bf16 v[36:39], v[206:209], v[180:183], v[36:39]
	v_mfma_f32_16x16x32_bf16 v[32:35], v[210:213], v[176:179], v[32:35]
	v_mfma_f32_16x16x32_bf16 v[32:35], v[214:217], v[180:183], v[32:35]
	v_mfma_f32_16x16x32_bf16 v[20:23], v[202:205], v[186:189], v[20:23]
	v_mfma_f32_16x16x32_bf16 v[20:23], v[206:209], v[190:193], v[20:23]
	v_mfma_f32_16x16x32_bf16 v[16:19], v[210:213], v[186:189], v[16:19]
	v_mfma_f32_16x16x32_bf16 v[16:19], v[214:217], v[190:193], v[16:19]
	v_mfma_f32_16x16x32_bf16 v[4:7], v[202:205], v[194:197], v[4:7]
	v_mfma_f32_16x16x32_bf16 v[4:7], v[206:209], v[198:201], v[4:7]
	v_mfma_f32_16x16x32_bf16 v[0:3], v[210:213], v[194:197], v[0:3]
	v_mfma_f32_16x16x32_bf16 v[0:3], v[214:217], v[198:201], v[0:3]
	s_add_i32 s62, 0, 0x18000
	v_add_u32_e32 v140, s62, v169
	s_barrier
	ds_read_b128 v[128:131], v140
	ds_read_b128 v[132:135], v140 offset:1024
	ds_read_b128 v[136:139], v140 offset:2048
	ds_read_b128 v[140:143], v140 offset:3072
	s_add_u32 s42, s42, 0x100000
	s_addc_u32 s43, s43, 0
	s_mov_b32 m0, s45
	v_lshl_add_u64 v[202:203], s[42:43], 0, v[144:145]
	ds_read_b128 v[160:163], v173 offset:32768
	ds_read_b128 v[164:167], v173 offset:33792
	ds_read_b128 v[176:179], v173 offset:34816
	ds_read_b128 v[180:183], v173 offset:35840
	ds_read_b128 v[186:189], v173 offset:36864
	ds_read_b128 v[190:193], v173 offset:37888
	ds_read_b128 v[194:197], v173 offset:38912
	ds_read_b128 v[198:201], v173 offset:39936
	global_load_lds_dwordx4 v[202:203], off
	v_lshl_add_u64 v[202:203], s[42:43], 0, v[148:149]
	s_mov_b32 m0, s46
	s_nop 0
	global_load_lds_dwordx4 v[202:203], off
	s_waitcnt lgkmcnt(8)
	s_barrier
	s_waitcnt lgkmcnt(0)
	v_mfma_f32_16x16x32_bf16 v[124:127], v[128:131], v[160:163], v[124:127]
	v_mfma_f32_16x16x32_bf16 v[124:127], v[132:135], v[164:167], v[124:127]
	v_mfma_f32_16x16x32_bf16 v[120:123], v[136:139], v[160:163], v[120:123]
	v_mfma_f32_16x16x32_bf16 v[120:123], v[140:143], v[164:167], v[120:123]
	v_mfma_f32_16x16x32_bf16 v[108:111], v[128:131], v[176:179], v[108:111]
	v_mfma_f32_16x16x32_bf16 v[108:111], v[132:135], v[180:183], v[108:111]
	v_mfma_f32_16x16x32_bf16 v[104:107], v[136:139], v[176:179], v[104:107]
	v_mfma_f32_16x16x32_bf16 v[104:107], v[140:143], v[180:183], v[104:107]
	v_mfma_f32_16x16x32_bf16 v[92:95], v[128:131], v[186:189], v[92:95]
	v_mfma_f32_16x16x32_bf16 v[92:95], v[132:135], v[190:193], v[92:95]
	v_mfma_f32_16x16x32_bf16 v[88:91], v[136:139], v[186:189], v[88:91]
	v_mfma_f32_16x16x32_bf16 v[88:91], v[140:143], v[190:193], v[88:91]
	v_mfma_f32_16x16x32_bf16 v[76:79], v[128:131], v[194:197], v[76:79]
	v_mfma_f32_16x16x32_bf16 v[76:79], v[132:135], v[198:201], v[76:79]
	v_mfma_f32_16x16x32_bf16 v[72:75], v[136:139], v[194:197], v[72:75]
	v_mfma_f32_16x16x32_bf16 v[72:75], v[140:143], v[198:201], v[72:75]
	s_barrier
	s_add_i32 s42, 0, 0x1c000
	s_add_i32 s43, s62, s5
	v_add_u32_e32 v185, s42, v169
	v_lshl_add_u64 v[218:219], v[218:219], 0, s[22:23]
	s_mov_b32 m0, s43
	ds_read_b128 v[202:205], v185
	ds_read_b128 v[206:209], v185 offset:1024
	ds_read_b128 v[210:213], v185 offset:2048
	ds_read_b128 v[214:217], v185 offset:3072
	global_load_lds_dwordx4 v[218:219], off
	v_lshl_add_u64 v[218:219], v[220:221], 0, s[22:23]
	s_add_i32 m0, s43, 0x2000
	s_nop 0
	global_load_lds_dwordx4 v[218:219], off
	s_barrier
	s_waitcnt lgkmcnt(0)
	v_mfma_f32_16x16x32_bf16 v[116:119], v[202:205], v[160:163], v[116:119]
	v_mfma_f32_16x16x32_bf16 v[116:119], v[206:209], v[164:167], v[116:119]
	v_mfma_f32_16x16x32_bf16 v[112:115], v[210:213], v[160:163], v[112:115]
	v_mfma_f32_16x16x32_bf16 v[112:115], v[214:217], v[164:167], v[112:115]
	v_mfma_f32_16x16x32_bf16 v[100:103], v[202:205], v[176:179], v[100:103]
	v_mfma_f32_16x16x32_bf16 v[100:103], v[206:209], v[180:183], v[100:103]
	v_mfma_f32_16x16x32_bf16 v[96:99], v[210:213], v[176:179], v[96:99]
	v_mfma_f32_16x16x32_bf16 v[96:99], v[214:217], v[180:183], v[96:99]
	v_mfma_f32_16x16x32_bf16 v[84:87], v[202:205], v[186:189], v[84:87]
	v_mfma_f32_16x16x32_bf16 v[84:87], v[206:209], v[190:193], v[84:87]
	v_mfma_f32_16x16x32_bf16 v[80:83], v[210:213], v[186:189], v[80:83]
	v_mfma_f32_16x16x32_bf16 v[80:83], v[214:217], v[190:193], v[80:83]
	v_mfma_f32_16x16x32_bf16 v[68:71], v[202:205], v[194:197], v[68:71]
	v_mfma_f32_16x16x32_bf16 v[68:71], v[206:209], v[198:201], v[68:71]
	v_mfma_f32_16x16x32_bf16 v[64:67], v[210:213], v[194:197], v[64:67]
	v_mfma_f32_16x16x32_bf16 v[64:67], v[214:217], v[198:201], v[64:67]
	s_mov_b32 m0, s48
	v_lshl_add_u64 v[218:219], v[222:223], 0, s[22:23]
	s_barrier
	ds_read_b128 v[160:163], v173 offset:49152
	ds_read_b128 v[164:167], v173 offset:50176
	ds_read_b128 v[176:179], v173 offset:51200
	ds_read_b128 v[180:183], v173 offset:52224
	ds_read_b128 v[186:189], v173 offset:53248
	ds_read_b128 v[190:193], v173 offset:54272
	ds_read_b128 v[194:197], v173 offset:55296
	ds_read_b128 v[198:201], v173 offset:56320
	global_load_lds_dwordx4 v[218:219], off
	v_lshl_add_u64 v[218:219], v[224:225], 0, s[22:23]
	s_mov_b32 m0, s49
	s_nop 0
	global_load_lds_dwordx4 v[218:219], off
	s_barrier
	s_waitcnt lgkmcnt(0)
	v_mfma_f32_16x16x32_bf16 v[60:63], v[128:131], v[160:163], v[60:63]
	v_mfma_f32_16x16x32_bf16 v[60:63], v[132:135], v[164:167], v[60:63]
	v_mfma_f32_16x16x32_bf16 v[56:59], v[136:139], v[160:163], v[56:59]
	v_mfma_f32_16x16x32_bf16 v[56:59], v[140:143], v[164:167], v[56:59]
	v_mfma_f32_16x16x32_bf16 v[44:47], v[128:131], v[176:179], v[44:47]
	v_mfma_f32_16x16x32_bf16 v[44:47], v[132:135], v[180:183], v[44:47]
	v_mfma_f32_16x16x32_bf16 v[40:43], v[136:139], v[176:179], v[40:43]
	v_mfma_f32_16x16x32_bf16 v[40:43], v[140:143], v[180:183], v[40:43]
	v_mfma_f32_16x16x32_bf16 v[28:31], v[128:131], v[186:189], v[28:31]
	v_mfma_f32_16x16x32_bf16 v[28:31], v[132:135], v[190:193], v[28:31]
	v_mfma_f32_16x16x32_bf16 v[24:27], v[136:139], v[186:189], v[24:27]
	v_mfma_f32_16x16x32_bf16 v[24:27], v[140:143], v[190:193], v[24:27]
	v_mfma_f32_16x16x32_bf16 v[12:15], v[128:131], v[194:197], v[12:15]
	v_mfma_f32_16x16x32_bf16 v[12:15], v[132:135], v[198:201], v[12:15]
	v_mfma_f32_16x16x32_bf16 v[8:11], v[136:139], v[194:197], v[8:11]
	v_mfma_f32_16x16x32_bf16 v[8:11], v[140:143], v[198:201], v[8:11]
	s_barrier
	s_add_u32 s40, s40, 0x100080
	s_addc_u32 s41, s41, 0
	s_add_i32 s42, s42, s5
	v_lshl_add_u64 v[128:129], s[40:41], 0, v[146:147]
	s_mov_b32 m0, s42
	s_nop 0
	global_load_lds_dwordx4 v[128:129], off
	v_lshl_add_u64 v[128:129], s[40:41], 0, v[150:151]
	s_add_i32 m0, s42, 0x2000
	s_nop 0
	global_load_lds_dwordx4 v[128:129], off
	s_waitcnt vmcnt(6)
	s_barrier
	v_mfma_f32_16x16x32_bf16 v[52:55], v[202:205], v[160:163], v[52:55]
	v_mfma_f32_16x16x32_bf16 v[52:55], v[206:209], v[164:167], v[52:55]
	v_mfma_f32_16x16x32_bf16 v[48:51], v[210:213], v[160:163], v[48:51]
	v_mfma_f32_16x16x32_bf16 v[48:51], v[214:217], v[164:167], v[48:51]
	v_mfma_f32_16x16x32_bf16 v[36:39], v[202:205], v[176:179], v[36:39]
	v_mfma_f32_16x16x32_bf16 v[36:39], v[206:209], v[180:183], v[36:39]
	v_mfma_f32_16x16x32_bf16 v[32:35], v[210:213], v[176:179], v[32:35]
	v_mfma_f32_16x16x32_bf16 v[32:35], v[214:217], v[180:183], v[32:35]
	v_mfma_f32_16x16x32_bf16 v[20:23], v[202:205], v[186:189], v[20:23]
	v_mfma_f32_16x16x32_bf16 v[20:23], v[206:209], v[190:193], v[20:23]
	v_mfma_f32_16x16x32_bf16 v[16:19], v[210:213], v[186:189], v[16:19]
	v_mfma_f32_16x16x32_bf16 v[16:19], v[214:217], v[190:193], v[16:19]
	v_mfma_f32_16x16x32_bf16 v[4:7], v[202:205], v[194:197], v[4:7]
	v_mfma_f32_16x16x32_bf16 v[4:7], v[206:209], v[198:201], v[4:7]
	v_mfma_f32_16x16x32_bf16 v[0:3], v[210:213], v[194:197], v[0:3]
	v_mfma_f32_16x16x32_bf16 v[0:3], v[214:217], v[198:201], v[0:3]
	s_add_i32 s61, s61, 2
	s_add_u32 s38, s38, 0x100
	s_addc_u32 s39, s39, 0
	s_add_u32 s35, s35, 0x100
	s_addc_u32 s55, s55, 0
	s_cmp_gt_u32 s61, 61
	s_barrier
	s_cbranch_scc0 .LBB0_514
	v_lshl_add_u32 v162, s34, 8, v168
	v_lshl_or_b32 v160, s36, 8, v170
	v_ashrrev_i32_e32 v163, 31, v162
	v_ashrrev_i32_e32 v161, 31, v160
	v_lshlrev_b64 v[128:129], 14, v[162:163]
	v_lshl_add_u64 v[128:129], s[12:13], 0, v[128:129]
	v_lshlrev_b64 v[130:131], 2, v[160:161]
	v_lshl_add_u64 v[128:129], v[128:129], 0, v[130:131]
	global_load_dwordx4 v[178:181], v[128:129], off
	global_load_dwordx4 v[186:189], v[128:129], off offset:16
	global_load_dwordx4 v[190:193], v[128:129], off offset:512
	global_load_dwordx4 v[194:197], v[128:129], off offset:528
	v_or_b32_e32 v164, 16, v162
	v_ashrrev_i32_e32 v165, 31, v164
	v_lshlrev_b64 v[128:129], 14, v[164:165]
	v_lshl_add_u64 v[128:129], s[12:13], 0, v[128:129]
	v_lshl_add_u64 v[132:133], v[128:129], 0, v[130:131]
	global_load_dwordx4 v[136:139], v[132:133], off offset:16
	global_load_dwordx4 v[140:143], v[132:133], off
	global_load_dwordx4 v[128:131], v[132:133], off offset:528
	s_nop 0
	global_load_dwordx4 v[132:135], v[132:133], off offset:512
	v_and_b32_e32 v166, 64, v175
	v_xor_b32_e32 v176, 16, v175
	v_add_u32_e32 v182, 64, v166
	v_xor_b32_e32 v177, 32, v175
	v_cmp_lt_i32_e32 vcc, v176, v182
	v_lshlrev_b64 v[166:167], 13, v[162:163]
	v_lshl_add_u64 v[166:167], s[56:57], 0, v[166:167]
	v_cndmask_b32_e32 v176, v175, v176, vcc
	v_cmp_lt_i32_e32 vcc, v177, v182
	v_lshlrev_b32_e32 v176, 2, v176
	v_lshl_add_u64 v[166:167], v[160:161], 1, v[166:167]
	v_cndmask_b32_e32 v177, v175, v177, vcc
	v_lshlrev_b32_e32 v177, 2, v177
	s_waitcnt vmcnt(0)
	v_pk_add_f32 v[126:127], v[126:127], v[180:181]
	v_pk_add_f32 v[124:125], v[124:125], v[178:179]
	v_pk_add_f32 v[118:119], v[118:119], v[192:193]
	v_pk_add_f32 v[116:117], v[116:117], v[190:191]
	v_pk_add_f32 v[120:121], v[120:121], v[186:187]
	v_pk_add_f32 v[178:179], v[114:115], v[196:197]
	v_pk_add_f32 v[180:181], v[112:113], v[194:195]
	v_mul_f32_e32 v114, v125, v125
	v_mul_f32_e32 v115, v127, v127
	v_cvt_pk_bf16_f32 v112, v124, v125
	v_cvt_pk_bf16_f32 v113, v126, v127
	v_mul_f32_e32 v125, v117, v117
	v_mul_f32_e32 v127, v119, v119
	v_pk_add_f32 v[122:123], v[122:123], v[188:189]
	v_mul_f32_e32 v182, v121, v121
	v_mul_f32_e32 v185, v181, v181
	v_fmac_f32_e32 v114, v124, v124
	v_fmac_f32_e32 v115, v126, v126
	v_fmac_f32_e32 v125, v116, v116
	v_fmac_f32_e32 v127, v118, v118
	v_mul_f32_e32 v183, v123, v123
	v_mul_f32_e32 v186, v179, v179
	v_fmac_f32_e32 v182, v120, v120
	v_fmac_f32_e32 v185, v180, v180
	v_add_f32_e32 v114, v114, v115
	v_add_f32_e32 v115, v125, v127
	v_fmac_f32_e32 v183, v122, v122
	v_fmac_f32_e32 v186, v178, v178
	v_add_f32_e32 v114, v114, v182
	v_add_f32_e32 v115, v115, v185
	v_add_f32_e32 v114, v183, v114
	v_add_f32_e32 v115, v186, v115
	v_add_f32_e32 v124, v114, v115
	ds_bpermute_b32 v125, v176, v124
	v_cvt_pk_bf16_f32 v114, v120, v121
	v_cvt_pk_bf16_f32 v115, v122, v123
	global_store_dwordx4 v[166:167], v[112:115], off
	s_waitcnt lgkmcnt(0)
	s_nop 0
	v_add_f32_e32 v112, v124, v125
	ds_bpermute_b32 v113, v177, v112
	v_cvt_pk_bf16_f32 v114, v116, v117
	v_cvt_pk_bf16_f32 v115, v118, v119
	v_cvt_pk_bf16_f32 v116, v180, v181
	v_cvt_pk_bf16_f32 v117, v178, v179
	global_store_dwordx4 v[166:167], v[114:117], off offset:256
	s_and_saveexec_b64 s[34:35], s[8:9]
	s_cbranch_execz .LBB0_517
	v_lshl_add_u64 v[114:115], v[162:163], 2, s[20:21]
	s_waitcnt lgkmcnt(0)
	v_add_f32_e32 v112, v112, v113
	global_atomic_add_f32 v[114:115], v112, off

.LBB0_604:
	ds_read_b128 v[16:19], v176
	ds_read_b128 v[20:23], v176 offset:1024
	ds_read_b128 v[32:35], v176 offset:2048
	ds_read_b128 v[36:39], v176 offset:3072
	s_add_u32 s41, s10, 0xfff00080
	s_addc_u32 s46, s11, -1
	s_cmp_eq_u32 s39, 60
	s_cselect_b32 s49, s4, s46
	s_cselect_b32 s48, s5, s41
	s_cselect_b32 s47, s6, s15
	s_cselect_b32 s46, s7, s13
	v_lshl_add_u64 v[160:161], s[10:11], 0, v[152:153]
	s_add_i32 m0, s52, 0xc000
	ds_read_b128 v[164:167], v177
	ds_read_b128 v[168:171], v177 offset:1024
	ds_read_b128 v[190:193], v177 offset:2048
	ds_read_b128 v[194:197], v177 offset:3072
	ds_read_b128 v[198:201], v177 offset:4096
	ds_read_b128 v[202:205], v177 offset:5120
	ds_read_b128 v[206:209], v177 offset:6144
	ds_read_b128 v[210:213], v177 offset:7168
	global_load_lds_dwordx4 v[160:161], off
	v_lshl_add_u64 v[160:161], s[10:11], 0, v[154:155]
	s_add_i32 m0, s52, 0xe000
	s_nop 0
	global_load_lds_dwordx4 v[160:161], off
	s_waitcnt lgkmcnt(8)
	s_barrier
	s_waitcnt lgkmcnt(0)
	v_mfma_f32_16x16x32_bf16 v[140:143], v[16:19], v[164:167], v[140:143]
	v_mfma_f32_16x16x32_bf16 v[140:143], v[20:23], v[168:171], v[140:143]
	v_mfma_f32_16x16x32_bf16 v[136:139], v[32:35], v[164:167], v[136:139]
	v_mfma_f32_16x16x32_bf16 v[136:139], v[36:39], v[168:171], v[136:139]
	v_mfma_f32_16x16x32_bf16 v[124:127], v[16:19], v[190:193], v[124:127]
	v_mfma_f32_16x16x32_bf16 v[124:127], v[20:23], v[194:197], v[124:127]
	v_mfma_f32_16x16x32_bf16 v[120:123], v[32:35], v[190:193], v[120:123]
	v_mfma_f32_16x16x32_bf16 v[120:123], v[36:39], v[194:197], v[120:123]
	v_mfma_f32_16x16x32_bf16 v[108:111], v[16:19], v[198:201], v[108:111]
	v_mfma_f32_16x16x32_bf16 v[108:111], v[20:23], v[202:205], v[108:111]
	v_mfma_f32_16x16x32_bf16 v[104:107], v[32:35], v[198:201], v[104:107]
	v_mfma_f32_16x16x32_bf16 v[104:107], v[36:39], v[202:205], v[104:107]
	v_mfma_f32_16x16x32_bf16 v[92:95], v[16:19], v[206:209], v[92:95]
	v_mfma_f32_16x16x32_bf16 v[92:95], v[20:23], v[210:213], v[92:95]
	v_mfma_f32_16x16x32_bf16 v[88:91], v[32:35], v[206:209], v[88:91]
	v_mfma_f32_16x16x32_bf16 v[88:91], v[36:39], v[210:213], v[88:91]
	s_barrier
	s_add_i32 s41, s81, s51
	v_lshl_add_u64 v[160:161], s[46:47], 0, v[146:147]
	s_mov_b32 m0, s41
	ds_read_b128 v[214:217], v178
	ds_read_b128 v[218:221], v178 offset:1024
	ds_read_b128 v[222:225], v178 offset:2048
	ds_read_b128 v[226:229], v178 offset:3072
	global_load_lds_dwordx4 v[160:161], off
	v_lshl_add_u64 v[230:231], s[46:47], 0, v[150:151]
	s_add_i32 m0, s41, 0x2000
	s_nop 0
	global_load_lds_dwordx4 v[230:231], off
	s_barrier
	s_waitcnt lgkmcnt(0)
	v_mfma_f32_16x16x32_bf16 v[132:135], v[214:217], v[164:167], v[132:135]
	v_mfma_f32_16x16x32_bf16 v[132:135], v[218:221], v[168:171], v[132:135]
	v_mfma_f32_16x16x32_bf16 v[128:131], v[222:225], v[164:167], v[128:131]
	v_mfma_f32_16x16x32_bf16 v[128:131], v[226:229], v[168:171], v[128:131]
	v_mfma_f32_16x16x32_bf16 v[116:119], v[214:217], v[190:193], v[116:119]
	v_mfma_f32_16x16x32_bf16 v[116:119], v[218:221], v[194:197], v[116:119]
	v_mfma_f32_16x16x32_bf16 v[112:115], v[222:225], v[190:193], v[112:115]
	v_mfma_f32_16x16x32_bf16 v[112:115], v[226:229], v[194:197], v[112:115]
	v_mfma_f32_16x16x32_bf16 v[100:103], v[214:217], v[198:201], v[100:103]
	v_mfma_f32_16x16x32_bf16 v[100:103], v[218:221], v[202:205], v[100:103]
	v_mfma_f32_16x16x32_bf16 v[96:99], v[222:225], v[198:201], v[96:99]
	v_mfma_f32_16x16x32_bf16 v[96:99], v[226:229], v[202:205], v[96:99]
	v_mfma_f32_16x16x32_bf16 v[84:87], v[214:217], v[206:209], v[84:87]
	v_mfma_f32_16x16x32_bf16 v[84:87], v[218:221], v[210:213], v[84:87]
	v_mfma_f32_16x16x32_bf16 v[80:83], v[222:225], v[206:209], v[80:83]
	v_mfma_f32_16x16x32_bf16 v[80:83], v[226:229], v[210:213], v[80:83]
	s_mov_b32 m0, s52
	v_lshl_add_u64 v[232:233], s[48:49], 0, v[144:145]
	s_barrier
	ds_read_b128 v[164:167], v177 offset:16384
	ds_read_b128 v[168:171], v177 offset:17408
	ds_read_b128 v[190:193], v177 offset:18432
	ds_read_b128 v[194:197], v177 offset:19456
	ds_read_b128 v[198:201], v177 offset:20480
	ds_read_b128 v[202:205], v177 offset:21504
	ds_read_b128 v[206:209], v177 offset:22528
	ds_read_b128 v[210:213], v177 offset:23552
	global_load_lds_dwordx4 v[232:233], off
	v_lshl_add_u64 v[234:235], s[48:49], 0, v[148:149]
	s_mov_b32 m0, s53
	s_nop 0
	global_load_lds_dwordx4 v[234:235], off
	s_barrier
	s_waitcnt lgkmcnt(0)
	v_mfma_f32_16x16x32_bf16 v[76:79], v[16:19], v[164:167], v[76:79]
	v_mfma_f32_16x16x32_bf16 v[76:79], v[20:23], v[168:171], v[76:79]
	v_mfma_f32_16x16x32_bf16 v[72:75], v[32:35], v[164:167], v[72:75]
	v_mfma_f32_16x16x32_bf16 v[72:75], v[36:39], v[168:171], v[72:75]
	v_mfma_f32_16x16x32_bf16 v[60:63], v[16:19], v[190:193], v[60:63]
	v_mfma_f32_16x16x32_bf16 v[60:63], v[20:23], v[194:197], v[60:63]
	v_mfma_f32_16x16x32_bf16 v[56:59], v[32:35], v[190:193], v[56:59]
	v_mfma_f32_16x16x32_bf16 v[56:59], v[36:39], v[194:197], v[56:59]
	v_mfma_f32_16x16x32_bf16 v[44:47], v[16:19], v[198:201], v[44:47]
	v_mfma_f32_16x16x32_bf16 v[44:47], v[20:23], v[202:205], v[44:47]
	v_mfma_f32_16x16x32_bf16 v[40:43], v[32:35], v[198:201], v[40:43]
	v_mfma_f32_16x16x32_bf16 v[40:43], v[36:39], v[202:205], v[40:43]
	v_mfma_f32_16x16x32_bf16 v[12:15], v[16:19], v[206:209], v[12:15]
	v_mfma_f32_16x16x32_bf16 v[12:15], v[20:23], v[210:213], v[12:15]
	v_mfma_f32_16x16x32_bf16 v[8:11], v[32:35], v[206:209], v[8:11]
	v_mfma_f32_16x16x32_bf16 v[8:11], v[36:39], v[210:213], v[8:11]
	s_barrier
	s_add_u32 s54, s46, 0x100000
	s_addc_u32 s55, s47, 0
	s_add_i32 s41, s82, s51
	v_lshl_add_u64 v[16:17], s[54:55], 0, v[146:147]
	s_mov_b32 m0, s41
	s_nop 0
	global_load_lds_dwordx4 v[16:17], off
	v_lshl_add_u64 v[16:17], s[54:55], 0, v[150:151]
	s_add_i32 m0, s41, 0x2000
	s_nop 0
	global_load_lds_dwordx4 v[16:17], off
	s_waitcnt vmcnt(6)
	s_barrier
	v_mfma_f32_16x16x32_bf16 v[28:31], v[214:217], v[198:201], v[28:31]
	v_mfma_f32_16x16x32_bf16 v[28:31], v[218:221], v[202:205], v[28:31]
	v_mfma_f32_16x16x32_bf16 v[24:27], v[222:225], v[198:201], v[24:27]
	v_mfma_f32_16x16x32_bf16 v[24:27], v[226:229], v[202:205], v[24:27]
	v_mfma_f32_16x16x32_bf16 v[4:7], v[214:217], v[206:209], v[4:7]
	v_mfma_f32_16x16x32_bf16 v[4:7], v[218:221], v[210:213], v[4:7]
	v_mfma_f32_16x16x32_bf16 v[0:3], v[222:225], v[206:209], v[0:3]
	v_mfma_f32_16x16x32_bf16 v[0:3], v[226:229], v[210:213], v[0:3]
	v_mfma_f32_16x16x32_bf16 v[16:19], v[214:217], v[164:167], v[68:71]
	v_mfma_f32_16x16x32_bf16 v[16:19], v[218:221], v[168:171], v[16:19]
	v_mfma_f32_16x16x32_bf16 v[20:23], v[222:225], v[164:167], v[64:67]
	v_mfma_f32_16x16x32_bf16 v[20:23], v[226:229], v[168:171], v[20:23]
	v_mfma_f32_16x16x32_bf16 v[32:35], v[214:217], v[190:193], v[52:55]
	v_mfma_f32_16x16x32_bf16 v[32:35], v[218:221], v[194:197], v[32:35]
	v_mfma_f32_16x16x32_bf16 v[36:39], v[222:225], v[190:193], v[48:51]
	v_mfma_f32_16x16x32_bf16 v[36:39], v[226:229], v[194:197], v[36:39]
	s_add_i32 s41, 0, 0x18000
	v_add_u32_e32 v68, s41, v174
	s_barrier
	ds_read_b128 v[48:51], v68
	ds_read_b128 v[52:55], v68 offset:1024
	ds_read_b128 v[64:67], v68 offset:2048
	ds_read_b128 v[68:71], v68 offset:3072
	s_add_u32 s48, s48, 0x100000
	s_addc_u32 s49, s49, 0
	s_mov_b32 m0, s61
	v_lshl_add_u64 v[214:215], s[48:49], 0, v[144:145]
	ds_read_b128 v[164:167], v177 offset:32768
	ds_read_b128 v[168:171], v177 offset:33792
	ds_read_b128 v[190:193], v177 offset:34816
	ds_read_b128 v[194:197], v177 offset:35840
	ds_read_b128 v[198:201], v177 offset:36864
	ds_read_b128 v[202:205], v177 offset:37888
	ds_read_b128 v[206:209], v177 offset:38912
	ds_read_b128 v[210:213], v177 offset:39936
	global_load_lds_dwordx4 v[214:215], off
	v_lshl_add_u64 v[214:215], s[48:49], 0, v[148:149]
	s_mov_b32 m0, s74
	s_nop 0
	global_load_lds_dwordx4 v[214:215], off
	s_waitcnt lgkmcnt(8)
	s_barrier
	s_waitcnt lgkmcnt(0)
	v_mfma_f32_16x16x32_bf16 v[140:143], v[48:51], v[164:167], v[140:143]
	v_mfma_f32_16x16x32_bf16 v[140:143], v[52:55], v[168:171], v[140:143]
	v_mfma_f32_16x16x32_bf16 v[136:139], v[64:67], v[164:167], v[136:139]
	v_mfma_f32_16x16x32_bf16 v[136:139], v[68:71], v[168:171], v[136:139]
	v_mfma_f32_16x16x32_bf16 v[124:127], v[48:51], v[190:193], v[124:127]
	v_mfma_f32_16x16x32_bf16 v[124:127], v[52:55], v[194:197], v[124:127]
	v_mfma_f32_16x16x32_bf16 v[120:123], v[64:67], v[190:193], v[120:123]
	v_mfma_f32_16x16x32_bf16 v[120:123], v[68:71], v[194:197], v[120:123]
	v_mfma_f32_16x16x32_bf16 v[108:111], v[48:51], v[198:201], v[108:111]
	v_mfma_f32_16x16x32_bf16 v[108:111], v[52:55], v[202:205], v[108:111]
	v_mfma_f32_16x16x32_bf16 v[104:107], v[64:67], v[198:201], v[104:107]
	v_mfma_f32_16x16x32_bf16 v[104:107], v[68:71], v[202:205], v[104:107]
	v_mfma_f32_16x16x32_bf16 v[92:95], v[48:51], v[206:209], v[92:95]
	v_mfma_f32_16x16x32_bf16 v[92:95], v[52:55], v[210:213], v[92:95]
	v_mfma_f32_16x16x32_bf16 v[88:91], v[64:67], v[206:209], v[88:91]
	v_mfma_f32_16x16x32_bf16 v[88:91], v[68:71], v[210:213], v[88:91]
	s_barrier
	s_add_i32 s48, 0, 0x1c000
	s_add_i32 s41, s41, s51
	v_add_u32_e32 v163, s48, v174
	v_lshl_add_u64 v[160:161], v[160:161], 0, s[22:23]
	s_mov_b32 m0, s41
	ds_read_b128 v[214:217], v163
	ds_read_b128 v[218:221], v163 offset:1024
	ds_read_b128 v[222:225], v163 offset:2048
	ds_read_b128 v[226:229], v163 offset:3072
	global_load_lds_dwordx4 v[160:161], off
	v_lshl_add_u64 v[160:161], v[230:231], 0, s[22:23]
	s_add_i32 m0, s41, 0x2000
	s_nop 0
	global_load_lds_dwordx4 v[160:161], off
	s_barrier
	s_waitcnt lgkmcnt(0)
	v_mfma_f32_16x16x32_bf16 v[132:135], v[214:217], v[164:167], v[132:135]
	v_mfma_f32_16x16x32_bf16 v[132:135], v[218:221], v[168:171], v[132:135]
	v_mfma_f32_16x16x32_bf16 v[128:131], v[222:225], v[164:167], v[128:131]
	v_mfma_f32_16x16x32_bf16 v[128:131], v[226:229], v[168:171], v[128:131]
	v_mfma_f32_16x16x32_bf16 v[116:119], v[214:217], v[190:193], v[116:119]
	v_mfma_f32_16x16x32_bf16 v[116:119], v[218:221], v[194:197], v[116:119]
	v_mfma_f32_16x16x32_bf16 v[112:115], v[222:225], v[190:193], v[112:115]
	v_mfma_f32_16x16x32_bf16 v[112:115], v[226:229], v[194:197], v[112:115]
	v_mfma_f32_16x16x32_bf16 v[100:103], v[214:217], v[198:201], v[100:103]
	v_mfma_f32_16x16x32_bf16 v[100:103], v[218:221], v[202:205], v[100:103]
	v_mfma_f32_16x16x32_bf16 v[96:99], v[222:225], v[198:201], v[96:99]
	v_mfma_f32_16x16x32_bf16 v[96:99], v[226:229], v[202:205], v[96:99]
	v_mfma_f32_16x16x32_bf16 v[84:87], v[214:217], v[206:209], v[84:87]
	v_mfma_f32_16x16x32_bf16 v[84:87], v[218:221], v[210:213], v[84:87]
	v_mfma_f32_16x16x32_bf16 v[80:83], v[222:225], v[206:209], v[80:83]
	v_mfma_f32_16x16x32_bf16 v[80:83], v[226:229], v[210:213], v[80:83]
	s_mov_b32 m0, s76
	v_lshl_add_u64 v[160:161], v[232:233], 0, s[22:23]
	s_barrier
	ds_read_b128 v[164:167], v177 offset:49152
	ds_read_b128 v[168:171], v177 offset:50176
	ds_read_b128 v[190:193], v177 offset:51200
	ds_read_b128 v[194:197], v177 offset:52224
	ds_read_b128 v[198:201], v177 offset:53248
	ds_read_b128 v[202:205], v177 offset:54272
	ds_read_b128 v[206:209], v177 offset:55296
	ds_read_b128 v[210:213], v177 offset:56320
	global_load_lds_dwordx4 v[160:161], off
	v_lshl_add_u64 v[160:161], v[234:235], 0, s[22:23]
	s_mov_b32 m0, s77
	s_nop 0
	global_load_lds_dwordx4 v[160:161], off
	s_barrier
	s_waitcnt lgkmcnt(0)
	v_mfma_f32_16x16x32_bf16 v[76:79], v[48:51], v[164:167], v[76:79]
	v_mfma_f32_16x16x32_bf16 v[76:79], v[52:55], v[168:171], v[76:79]
	v_mfma_f32_16x16x32_bf16 v[72:75], v[64:67], v[164:167], v[72:75]
	v_mfma_f32_16x16x32_bf16 v[72:75], v[68:71], v[168:171], v[72:75]
	v_mfma_f32_16x16x32_bf16 v[60:63], v[48:51], v[190:193], v[60:63]
	v_mfma_f32_16x16x32_bf16 v[60:63], v[52:55], v[194:197], v[60:63]
	v_mfma_f32_16x16x32_bf16 v[56:59], v[64:67], v[190:193], v[56:59]
	v_mfma_f32_16x16x32_bf16 v[56:59], v[68:71], v[194:197], v[56:59]
	v_mfma_f32_16x16x32_bf16 v[44:47], v[48:51], v[198:201], v[44:47]
	v_mfma_f32_16x16x32_bf16 v[44:47], v[52:55], v[202:205], v[44:47]
	v_mfma_f32_16x16x32_bf16 v[40:43], v[64:67], v[198:201], v[40:43]
	v_mfma_f32_16x16x32_bf16 v[40:43], v[68:71], v[202:205], v[40:43]
	v_mfma_f32_16x16x32_bf16 v[12:15], v[48:51], v[206:209], v[12:15]
	v_mfma_f32_16x16x32_bf16 v[12:15], v[52:55], v[210:213], v[12:15]
	v_mfma_f32_16x16x32_bf16 v[8:11], v[64:67], v[206:209], v[8:11]
	v_mfma_f32_16x16x32_bf16 v[8:11], v[68:71], v[210:213], v[8:11]
	s_barrier
	s_add_u32 s46, s46, 0x100080
	s_addc_u32 s47, s47, 0
	s_add_i32 s41, s48, s51
	v_lshl_add_u64 v[48:49], s[46:47], 0, v[146:147]
	s_mov_b32 m0, s41
	s_nop 0
	global_load_lds_dwordx4 v[48:49], off
	v_lshl_add_u64 v[48:49], s[46:47], 0, v[150:151]
	s_add_i32 m0, s41, 0x2000
	s_nop 0
	global_load_lds_dwordx4 v[48:49], off
	s_waitcnt vmcnt(6)
	s_barrier
	v_mfma_f32_16x16x32_bf16 v[16:19], v[214:217], v[164:167], v[16:19]
	v_mfma_f32_16x16x32_bf16 v[68:71], v[218:221], v[168:171], v[16:19]
	v_mfma_f32_16x16x32_bf16 v[16:19], v[222:225], v[164:167], v[20:23]
	v_mfma_f32_16x16x32_bf16 v[64:67], v[226:229], v[168:171], v[16:19]
	v_mfma_f32_16x16x32_bf16 v[16:19], v[214:217], v[190:193], v[32:35]
	v_mfma_f32_16x16x32_bf16 v[52:55], v[218:221], v[194:197], v[16:19]
	v_mfma_f32_16x16x32_bf16 v[16:19], v[222:225], v[190:193], v[36:39]
	v_mfma_f32_16x16x32_bf16 v[48:51], v[226:229], v[194:197], v[16:19]
	v_mfma_f32_16x16x32_bf16 v[16:19], v[214:217], v[198:201], v[28:31]
	v_mfma_f32_16x16x32_bf16 v[28:31], v[218:221], v[202:205], v[16:19]
	v_mfma_f32_16x16x32_bf16 v[16:19], v[222:225], v[198:201], v[24:27]
	v_mfma_f32_16x16x32_bf16 v[24:27], v[226:229], v[202:205], v[16:19]
	v_mfma_f32_16x16x32_bf16 v[4:7], v[214:217], v[206:209], v[4:7]
	v_mfma_f32_16x16x32_bf16 v[4:7], v[218:221], v[210:213], v[4:7]
	v_mfma_f32_16x16x32_bf16 v[0:3], v[222:225], v[206:209], v[0:3]
	v_mfma_f32_16x16x32_bf16 v[0:3], v[226:229], v[210:213], v[0:3]
	s_add_i32 s39, s39, 2
	s_add_u32 s10, s10, 0x100
	s_addc_u32 s11, s11, 0
	s_add_u32 s13, s13, 0x100
	s_addc_u32 s15, s15, 0
	s_cmp_gt_u32 s39, 61
	s_barrier
	s_cbranch_scc0 .LBB0_604
	s_ashr_i32 s4, s12, 4
	s_cmp_eq_u32 s4, 1
	v_lshl_or_b32 v160, s12, 8, v175
	v_mov_b32_e32 v36, 0
	s_cselect_b64 s[46:47], -1, 0
	s_cmp_lg_u32 s4, 1
	v_mov_b32_e32 v37, 0
	v_mov_b32_e32 v38, 0
	v_mov_b32_e32 v39, 0
	v_mov_b32_e32 v32, 0
	v_mov_b32_e32 v33, 0
	v_mov_b32_e32 v34, 0
	v_mov_b32_e32 v35, 0
	v_mov_b32_e32 v20, 0
	v_mov_b32_e32 v21, 0
	v_mov_b32_e32 v22, 0
	v_mov_b32_e32 v23, 0
	v_mov_b32_e32 v16, 0
	v_mov_b32_e32 v17, 0
	v_mov_b32_e32 v18, 0
	v_mov_b32_e32 v19, 0
	s_cbranch_scc1 .LBB0_607
	v_mov_b32_e32 v161, v147
	v_lshl_add_u64 v[16:17], v[160:161], 2, s[18:19]
	v_add_co_u32_e32 v20, vcc, 0xffffc000, v16
	v_lshl_add_u64 v[18:19], v[16:17], 0, s[24:25]
	s_nop 0
	v_addc_co_u32_e32 v21, vcc, -1, v17, vcc
	global_load_dwordx4 v[36:39], v[20:21], off
	global_load_dwordx4 v[32:35], v[18:19], off offset:16
	v_lshl_add_u64 v[18:19], v[16:17], 0, s[26:27]
	v_add_co_u32_e32 v16, vcc, 0xffffd000, v16
	s_nop 1
	v_addc_co_u32_e32 v17, vcc, -1, v17, vcc
	global_load_dwordx4 v[20:23], v[16:17], off offset:-3584
	s_nop 0
	global_load_dwordx4 v[16:19], v[18:19], off offset:16

.LBB0_981:
	ds_read_b128 v[128:131], v163
	ds_read_b128 v[132:135], v163 offset:1024
	ds_read_b128 v[152:155], v163 offset:2048
	ds_read_b128 v[156:159], v163 offset:3072
	s_add_u32 s26, s24, 0xffc00080
	s_addc_u32 s27, s25, -1
	s_cmp_eq_u32 s47, 60
	s_cselect_b32 s29, s15, s27
	s_cselect_b32 s28, s21, s26
	s_cselect_b32 s27, s13, s46
	s_cselect_b32 s26, s44, s45
	v_lshl_add_u64 v[182:183], s[24:25], 0, v[144:145]
	s_add_i32 m0, s23, 0xc000
	ds_read_b128 v[168:171], v164
	ds_read_b128 v[174:177], v164 offset:1024
	ds_read_b128 v[178:181], v164 offset:2048
	ds_read_b128 v[186:189], v164 offset:3072
	ds_read_b128 v[190:193], v164 offset:4096
	ds_read_b128 v[194:197], v164 offset:5120
	ds_read_b128 v[198:201], v164 offset:6144
	ds_read_b128 v[202:205], v164 offset:7168
	global_load_lds_dwordx4 v[182:183], off
	v_lshl_add_u64 v[182:183], s[24:25], 0, v[146:147]
	s_add_i32 m0, s23, 0xe000
	s_nop 0
	global_load_lds_dwordx4 v[182:183], off
	s_waitcnt lgkmcnt(8)
	s_barrier
	s_waitcnt lgkmcnt(0)
	v_mfma_f32_16x16x32_bf16 v[124:127], v[128:131], v[168:171], v[124:127]
	v_mfma_f32_16x16x32_bf16 v[124:127], v[132:135], v[174:177], v[124:127]
	v_mfma_f32_16x16x32_bf16 v[120:123], v[152:155], v[168:171], v[120:123]
	v_mfma_f32_16x16x32_bf16 v[120:123], v[156:159], v[174:177], v[120:123]
	v_mfma_f32_16x16x32_bf16 v[108:111], v[128:131], v[178:181], v[108:111]
	v_mfma_f32_16x16x32_bf16 v[108:111], v[132:135], v[186:189], v[108:111]
	v_mfma_f32_16x16x32_bf16 v[104:107], v[152:155], v[178:181], v[104:107]
	v_mfma_f32_16x16x32_bf16 v[104:107], v[156:159], v[186:189], v[104:107]
	v_mfma_f32_16x16x32_bf16 v[92:95], v[128:131], v[190:193], v[92:95]
	v_mfma_f32_16x16x32_bf16 v[92:95], v[132:135], v[194:197], v[92:95]
	v_mfma_f32_16x16x32_bf16 v[88:91], v[152:155], v[190:193], v[88:91]
	v_mfma_f32_16x16x32_bf16 v[88:91], v[156:159], v[194:197], v[88:91]
	v_mfma_f32_16x16x32_bf16 v[76:79], v[128:131], v[198:201], v[76:79]
	v_mfma_f32_16x16x32_bf16 v[76:79], v[132:135], v[202:205], v[76:79]
	v_mfma_f32_16x16x32_bf16 v[72:75], v[152:155], v[198:201], v[72:75]
	v_mfma_f32_16x16x32_bf16 v[72:75], v[156:159], v[202:205], v[72:75]
	s_barrier
	s_add_i32 s48, s42, s30
	v_lshl_add_u64 v[182:183], s[26:27], 0, v[138:139]
	s_mov_b32 m0, s48
	ds_read_b128 v[206:209], v165
	ds_read_b128 v[210:213], v165 offset:1024
	ds_read_b128 v[214:217], v165 offset:2048
	ds_read_b128 v[218:221], v165 offset:3072
	global_load_lds_dwordx4 v[182:183], off
	v_lshl_add_u64 v[222:223], s[26:27], 0, v[142:143]
	s_add_i32 m0, s48, 0x2000
	s_nop 0
	global_load_lds_dwordx4 v[222:223], off
	s_barrier
	s_waitcnt lgkmcnt(0)
	v_mfma_f32_16x16x32_bf16 v[116:119], v[206:209], v[168:171], v[116:119]
	v_mfma_f32_16x16x32_bf16 v[116:119], v[210:213], v[174:177], v[116:119]
	v_mfma_f32_16x16x32_bf16 v[112:115], v[214:217], v[168:171], v[112:115]
	v_mfma_f32_16x16x32_bf16 v[112:115], v[218:221], v[174:177], v[112:115]
	v_mfma_f32_16x16x32_bf16 v[100:103], v[206:209], v[178:181], v[100:103]
	v_mfma_f32_16x16x32_bf16 v[100:103], v[210:213], v[186:189], v[100:103]
	v_mfma_f32_16x16x32_bf16 v[96:99], v[214:217], v[178:181], v[96:99]
	v_mfma_f32_16x16x32_bf16 v[96:99], v[218:221], v[186:189], v[96:99]
	v_mfma_f32_16x16x32_bf16 v[84:87], v[206:209], v[190:193], v[84:87]
	v_mfma_f32_16x16x32_bf16 v[84:87], v[210:213], v[194:197], v[84:87]
	v_mfma_f32_16x16x32_bf16 v[80:83], v[214:217], v[190:193], v[80:83]
	v_mfma_f32_16x16x32_bf16 v[80:83], v[218:221], v[194:197], v[80:83]
	v_mfma_f32_16x16x32_bf16 v[68:71], v[206:209], v[198:201], v[68:71]
	v_mfma_f32_16x16x32_bf16 v[68:71], v[210:213], v[202:205], v[68:71]
	v_mfma_f32_16x16x32_bf16 v[64:67], v[214:217], v[198:201], v[64:67]
	v_mfma_f32_16x16x32_bf16 v[64:67], v[218:221], v[202:205], v[64:67]
	s_mov_b32 m0, s23
	v_lshl_add_u64 v[224:225], s[28:29], 0, v[136:137]
	s_barrier
	ds_read_b128 v[168:171], v164 offset:16384
	ds_read_b128 v[174:177], v164 offset:17408
	ds_read_b128 v[178:181], v164 offset:18432
	ds_read_b128 v[186:189], v164 offset:19456
	ds_read_b128 v[190:193], v164 offset:20480
	ds_read_b128 v[194:197], v164 offset:21504
	ds_read_b128 v[198:201], v164 offset:22528
	ds_read_b128 v[202:205], v164 offset:23552
	global_load_lds_dwordx4 v[224:225], off
	v_lshl_add_u64 v[226:227], s[28:29], 0, v[140:141]
	s_mov_b32 m0, s31
	s_nop 0
	global_load_lds_dwordx4 v[226:227], off
	s_barrier
	s_waitcnt lgkmcnt(0)
	v_mfma_f32_16x16x32_bf16 v[60:63], v[128:131], v[168:171], v[60:63]
	v_mfma_f32_16x16x32_bf16 v[60:63], v[132:135], v[174:177], v[60:63]
	v_mfma_f32_16x16x32_bf16 v[56:59], v[152:155], v[168:171], v[56:59]
	v_mfma_f32_16x16x32_bf16 v[56:59], v[156:159], v[174:177], v[56:59]
	v_mfma_f32_16x16x32_bf16 v[44:47], v[128:131], v[178:181], v[44:47]
	v_mfma_f32_16x16x32_bf16 v[44:47], v[132:135], v[186:189], v[44:47]
	v_mfma_f32_16x16x32_bf16 v[40:43], v[152:155], v[178:181], v[40:43]
	v_mfma_f32_16x16x32_bf16 v[40:43], v[156:159], v[186:189], v[40:43]
	v_mfma_f32_16x16x32_bf16 v[28:31], v[128:131], v[190:193], v[28:31]
	v_mfma_f32_16x16x32_bf16 v[28:31], v[132:135], v[194:197], v[28:31]
	v_mfma_f32_16x16x32_bf16 v[24:27], v[152:155], v[190:193], v[24:27]
	v_mfma_f32_16x16x32_bf16 v[24:27], v[156:159], v[194:197], v[24:27]
	v_mfma_f32_16x16x32_bf16 v[12:15], v[128:131], v[198:201], v[12:15]
	v_mfma_f32_16x16x32_bf16 v[12:15], v[132:135], v[202:205], v[12:15]
	v_mfma_f32_16x16x32_bf16 v[8:11], v[152:155], v[198:201], v[8:11]
	v_mfma_f32_16x16x32_bf16 v[8:11], v[156:159], v[202:205], v[8:11]
	s_barrier
	s_add_u32 s48, s26, 0x100000
	s_addc_u32 s49, s27, 0
	s_add_i32 s50, s43, s30
	v_lshl_add_u64 v[128:129], s[48:49], 0, v[138:139]
	s_mov_b32 m0, s50
	s_nop 0
	global_load_lds_dwordx4 v[128:129], off
	v_lshl_add_u64 v[128:129], s[48:49], 0, v[142:143]
	s_add_i32 m0, s50, 0x2000
	s_nop 0
	global_load_lds_dwordx4 v[128:129], off
	s_waitcnt vmcnt(6)
	s_barrier
	v_mfma_f32_16x16x32_bf16 v[52:55], v[206:209], v[168:171], v[52:55]
	v_mfma_f32_16x16x32_bf16 v[52:55], v[210:213], v[174:177], v[52:55]
	v_mfma_f32_16x16x32_bf16 v[48:51], v[214:217], v[168:171], v[48:51]
	v_mfma_f32_16x16x32_bf16 v[48:51], v[218:221], v[174:177], v[48:51]
	v_mfma_f32_16x16x32_bf16 v[36:39], v[206:209], v[178:181], v[36:39]
	v_mfma_f32_16x16x32_bf16 v[36:39], v[210:213], v[186:189], v[36:39]
	v_mfma_f32_16x16x32_bf16 v[32:35], v[214:217], v[178:181], v[32:35]
	v_mfma_f32_16x16x32_bf16 v[32:35], v[218:221], v[186:189], v[32:35]
	v_mfma_f32_16x16x32_bf16 v[20:23], v[206:209], v[190:193], v[20:23]
	v_mfma_f32_16x16x32_bf16 v[20:23], v[210:213], v[194:197], v[20:23]
	v_mfma_f32_16x16x32_bf16 v[16:19], v[214:217], v[190:193], v[16:19]
	v_mfma_f32_16x16x32_bf16 v[16:19], v[218:221], v[194:197], v[16:19]
	v_mfma_f32_16x16x32_bf16 v[4:7], v[206:209], v[198:201], v[4:7]
	v_mfma_f32_16x16x32_bf16 v[4:7], v[210:213], v[202:205], v[4:7]
	v_mfma_f32_16x16x32_bf16 v[0:3], v[214:217], v[198:201], v[0:3]
	v_mfma_f32_16x16x32_bf16 v[0:3], v[218:221], v[202:205], v[0:3]
	s_add_i32 s48, 0, 0x18000
	v_add_u32_e32 v156, s48, v161
	s_barrier
	ds_read_b128 v[128:131], v156
	ds_read_b128 v[132:135], v156 offset:1024
	ds_read_b128 v[152:155], v156 offset:2048
	ds_read_b128 v[156:159], v156 offset:3072
	s_add_u32 s28, s28, 0x400000
	s_addc_u32 s29, s29, 0
	s_mov_b32 m0, s34
	v_lshl_add_u64 v[206:207], s[28:29], 0, v[136:137]
	ds_read_b128 v[168:171], v164 offset:32768
	ds_read_b128 v[174:177], v164 offset:33792
	ds_read_b128 v[178:181], v164 offset:34816
	ds_read_b128 v[186:189], v164 offset:35840
	ds_read_b128 v[190:193], v164 offset:36864
	ds_read_b128 v[194:197], v164 offset:37888
	ds_read_b128 v[198:201], v164 offset:38912
	ds_read_b128 v[202:205], v164 offset:39936
	global_load_lds_dwordx4 v[206:207], off
	v_lshl_add_u64 v[206:207], s[28:29], 0, v[140:141]
	s_mov_b32 m0, s35
	s_nop 0
	global_load_lds_dwordx4 v[206:207], off
	s_waitcnt lgkmcnt(8)
	s_barrier
	s_waitcnt lgkmcnt(0)
	v_mfma_f32_16x16x32_bf16 v[124:127], v[128:131], v[168:171], v[124:127]
	v_mfma_f32_16x16x32_bf16 v[124:127], v[132:135], v[174:177], v[124:127]
	v_mfma_f32_16x16x32_bf16 v[120:123], v[152:155], v[168:171], v[120:123]
	v_mfma_f32_16x16x32_bf16 v[120:123], v[156:159], v[174:177], v[120:123]
	v_mfma_f32_16x16x32_bf16 v[108:111], v[128:131], v[178:181], v[108:111]
	v_mfma_f32_16x16x32_bf16 v[108:111], v[132:135], v[186:189], v[108:111]
	v_mfma_f32_16x16x32_bf16 v[104:107], v[152:155], v[178:181], v[104:107]
	v_mfma_f32_16x16x32_bf16 v[104:107], v[156:159], v[186:189], v[104:107]
	v_mfma_f32_16x16x32_bf16 v[92:95], v[128:131], v[190:193], v[92:95]
	v_mfma_f32_16x16x32_bf16 v[92:95], v[132:135], v[194:197], v[92:95]
	v_mfma_f32_16x16x32_bf16 v[88:91], v[152:155], v[190:193], v[88:91]
	v_mfma_f32_16x16x32_bf16 v[88:91], v[156:159], v[194:197], v[88:91]
	v_mfma_f32_16x16x32_bf16 v[76:79], v[128:131], v[198:201], v[76:79]
	v_mfma_f32_16x16x32_bf16 v[76:79], v[132:135], v[202:205], v[76:79]
	v_mfma_f32_16x16x32_bf16 v[72:75], v[152:155], v[198:201], v[72:75]
	v_mfma_f32_16x16x32_bf16 v[72:75], v[156:159], v[202:205], v[72:75]
	s_barrier
	s_add_i32 s28, 0, 0x1c000
	s_add_i32 s29, s48, s30
	v_add_u32_e32 v167, s28, v161
	v_lshl_add_u64 v[182:183], v[182:183], 0, s[10:11]
	s_mov_b32 m0, s29
	ds_read_b128 v[206:209], v167
	ds_read_b128 v[210:213], v167 offset:1024
	ds_read_b128 v[214:217], v167 offset:2048
	ds_read_b128 v[218:221], v167 offset:3072
	global_load_lds_dwordx4 v[182:183], off
	v_lshl_add_u64 v[182:183], v[222:223], 0, s[10:11]
	s_add_i32 m0, s29, 0x2000
	s_nop 0
	global_load_lds_dwordx4 v[182:183], off
	s_barrier
	s_waitcnt lgkmcnt(0)
	v_mfma_f32_16x16x32_bf16 v[116:119], v[206:209], v[168:171], v[116:119]
	v_mfma_f32_16x16x32_bf16 v[116:119], v[210:213], v[174:177], v[116:119]
	v_mfma_f32_16x16x32_bf16 v[112:115], v[214:217], v[168:171], v[112:115]
	v_mfma_f32_16x16x32_bf16 v[112:115], v[218:221], v[174:177], v[112:115]
	v_mfma_f32_16x16x32_bf16 v[100:103], v[206:209], v[178:181], v[100:103]
	v_mfma_f32_16x16x32_bf16 v[100:103], v[210:213], v[186:189], v[100:103]
	v_mfma_f32_16x16x32_bf16 v[96:99], v[214:217], v[178:181], v[96:99]
	v_mfma_f32_16x16x32_bf16 v[96:99], v[218:221], v[186:189], v[96:99]
	v_mfma_f32_16x16x32_bf16 v[84:87], v[206:209], v[190:193], v[84:87]
	v_mfma_f32_16x16x32_bf16 v[84:87], v[210:213], v[194:197], v[84:87]
	v_mfma_f32_16x16x32_bf16 v[80:83], v[214:217], v[190:193], v[80:83]
	v_mfma_f32_16x16x32_bf16 v[80:83], v[218:221], v[194:197], v[80:83]
	v_mfma_f32_16x16x32_bf16 v[68:71], v[206:209], v[198:201], v[68:71]
	v_mfma_f32_16x16x32_bf16 v[68:71], v[210:213], v[202:205], v[68:71]
	v_mfma_f32_16x16x32_bf16 v[64:67], v[214:217], v[198:201], v[64:67]
	v_mfma_f32_16x16x32_bf16 v[64:67], v[218:221], v[202:205], v[64:67]
	s_mov_b32 m0, s37
	v_lshl_add_u64 v[182:183], v[224:225], 0, s[10:11]
	s_barrier
	ds_read_b128 v[168:171], v164 offset:49152
	ds_read_b128 v[174:177], v164 offset:50176
	ds_read_b128 v[178:181], v164 offset:51200
	ds_read_b128 v[186:189], v164 offset:52224
	ds_read_b128 v[190:193], v164 offset:53248
	ds_read_b128 v[194:197], v164 offset:54272
	ds_read_b128 v[198:201], v164 offset:55296
	ds_read_b128 v[202:205], v164 offset:56320
	global_load_lds_dwordx4 v[182:183], off
	v_lshl_add_u64 v[182:183], v[226:227], 0, s[10:11]
	s_mov_b32 m0, s38
	s_nop 0
	global_load_lds_dwordx4 v[182:183], off
	s_barrier
	s_waitcnt lgkmcnt(0)
	v_mfma_f32_16x16x32_bf16 v[60:63], v[128:131], v[168:171], v[60:63]
	v_mfma_f32_16x16x32_bf16 v[60:63], v[132:135], v[174:177], v[60:63]
	v_mfma_f32_16x16x32_bf16 v[56:59], v[152:155], v[168:171], v[56:59]
	v_mfma_f32_16x16x32_bf16 v[56:59], v[156:159], v[174:177], v[56:59]
	v_mfma_f32_16x16x32_bf16 v[44:47], v[128:131], v[178:181], v[44:47]
	v_mfma_f32_16x16x32_bf16 v[44:47], v[132:135], v[186:189], v[44:47]
	v_mfma_f32_16x16x32_bf16 v[40:43], v[152:155], v[178:181], v[40:43]
	v_mfma_f32_16x16x32_bf16 v[40:43], v[156:159], v[186:189], v[40:43]
	v_mfma_f32_16x16x32_bf16 v[28:31], v[128:131], v[190:193], v[28:31]
	v_mfma_f32_16x16x32_bf16 v[28:31], v[132:135], v[194:197], v[28:31]
	v_mfma_f32_16x16x32_bf16 v[24:27], v[152:155], v[190:193], v[24:27]
	v_mfma_f32_16x16x32_bf16 v[24:27], v[156:159], v[194:197], v[24:27]
	v_mfma_f32_16x16x32_bf16 v[12:15], v[128:131], v[198:201], v[12:15]
	v_mfma_f32_16x16x32_bf16 v[12:15], v[132:135], v[202:205], v[12:15]
	v_mfma_f32_16x16x32_bf16 v[8:11], v[152:155], v[198:201], v[8:11]
	v_mfma_f32_16x16x32_bf16 v[8:11], v[156:159], v[202:205], v[8:11]
	s_barrier
	s_add_u32 s26, s26, 0x100080
	s_addc_u32 s27, s27, 0
	s_add_i32 s28, s28, s30
	v_lshl_add_u64 v[128:129], s[26:27], 0, v[138:139]
	s_mov_b32 m0, s28
	s_nop 0
	global_load_lds_dwordx4 v[128:129], off
	v_lshl_add_u64 v[128:129], s[26:27], 0, v[142:143]
	s_add_i32 m0, s28, 0x2000
	s_nop 0
	global_load_lds_dwordx4 v[128:129], off
	s_waitcnt vmcnt(6)
	s_barrier
	v_mfma_f32_16x16x32_bf16 v[52:55], v[206:209], v[168:171], v[52:55]
	v_mfma_f32_16x16x32_bf16 v[52:55], v[210:213], v[174:177], v[52:55]
	v_mfma_f32_16x16x32_bf16 v[48:51], v[214:217], v[168:171], v[48:51]
	v_mfma_f32_16x16x32_bf16 v[48:51], v[218:221], v[174:177], v[48:51]
	v_mfma_f32_16x16x32_bf16 v[36:39], v[206:209], v[178:181], v[36:39]
	v_mfma_f32_16x16x32_bf16 v[36:39], v[210:213], v[186:189], v[36:39]
	v_mfma_f32_16x16x32_bf16 v[32:35], v[214:217], v[178:181], v[32:35]
	v_mfma_f32_16x16x32_bf16 v[32:35], v[218:221], v[186:189], v[32:35]
	v_mfma_f32_16x16x32_bf16 v[20:23], v[206:209], v[190:193], v[20:23]
	v_mfma_f32_16x16x32_bf16 v[20:23], v[210:213], v[194:197], v[20:23]
	v_mfma_f32_16x16x32_bf16 v[16:19], v[214:217], v[190:193], v[16:19]
	v_mfma_f32_16x16x32_bf16 v[16:19], v[218:221], v[194:197], v[16:19]
	v_mfma_f32_16x16x32_bf16 v[4:7], v[206:209], v[198:201], v[4:7]
	v_mfma_f32_16x16x32_bf16 v[4:7], v[210:213], v[202:205], v[4:7]
	v_mfma_f32_16x16x32_bf16 v[0:3], v[214:217], v[198:201], v[0:3]
	v_mfma_f32_16x16x32_bf16 v[0:3], v[218:221], v[202:205], v[0:3]
	s_add_i32 s47, s47, 2
	s_add_u32 s24, s24, 0x100
	s_addc_u32 s25, s25, 0
	s_add_u32 s45, s45, 0x100
	s_addc_u32 s46, s46, 0
	s_cmp_gt_u32 s47, 61
	s_barrier
	s_cbranch_scc0 .LBB0_981
	v_lshl_add_u32 v156, s20, 8, v160
	v_lshl_or_b32 v152, s22, 8, v162
	v_ashrrev_i32_e32 v157, 31, v156
	v_ashrrev_i32_e32 v153, 31, v152
	v_lshlrev_b64 v[128:129], 13, v[156:157]
	v_lshl_add_u64 v[128:129], s[56:57], 0, v[128:129]
	v_lshlrev_b64 v[154:155], 1, v[152:153]
	v_lshl_add_u64 v[128:129], v[128:129], 0, v[154:155]
	global_load_dwordx4 v[168:171], v[128:129], off
	global_load_dwordx4 v[174:177], v[128:129], off offset:256
	v_or_b32_e32 v158, 16, v156
	v_ashrrev_i32_e32 v159, 31, v158
	v_lshlrev_b64 v[128:129], 13, v[158:159]
	v_lshl_add_u64 v[128:129], s[56:57], 0, v[128:129]
	v_lshl_add_u64 v[128:129], v[128:129], 0, v[154:155]
	global_load_dwordx4 v[132:135], v[128:129], off
	s_nop 0
	global_load_dwordx4 v[128:131], v[128:129], off offset:256
	v_and_b32_e32 v173, 64, v166
	v_xor_b32_e32 v167, 16, v166
	v_add_u32_e32 v173, 64, v173
	v_xor_b32_e32 v180, 32, v166
	v_cmp_lt_i32_e32 vcc, v167, v173
	v_lshlrev_b64 v[178:179], 15, v[156:157]
	v_lshl_add_u64 v[178:179], s[68:69], 0, v[178:179]
	v_cndmask_b32_e32 v167, v166, v167, vcc
	v_cmp_lt_i32_e32 vcc, v180, v173
	v_lshlrev_b32_e32 v167, 2, v167
	v_lshl_add_u64 v[178:179], v[178:179], 0, v[154:155]
	v_cndmask_b32_e32 v173, v166, v180, vcc
	s_waitcnt vmcnt(0)
	v_lshlrev_b32_e32 v180, 16, v168
	v_and_b32_e32 v181, 0xffff0000, v168
	v_lshlrev_b32_e32 v168, 16, v169
	v_and_b32_e32 v169, 0xffff0000, v169
	v_lshlrev_b32_e32 v186, 16, v174
	v_and_b32_e32 v187, 0xffff0000, v174
	v_lshlrev_b32_e32 v174, 16, v175
	v_and_b32_e32 v175, 0xffff0000, v175
	v_lshlrev_b32_e32 v182, 16, v170
	v_and_b32_e32 v183, 0xffff0000, v170
	v_lshlrev_b32_e32 v170, 16, v171
	v_and_b32_e32 v171, 0xffff0000, v171
	v_lshlrev_b32_e32 v188, 16, v176
	v_and_b32_e32 v189, 0xffff0000, v176
	v_lshlrev_b32_e32 v176, 16, v177
	v_and_b32_e32 v177, 0xffff0000, v177
	v_pk_add_f32 v[126:127], v[126:127], v[168:169]
	v_pk_add_f32 v[124:125], v[124:125], v[180:181]
	v_pk_add_f32 v[118:119], v[118:119], v[174:175]
	v_pk_add_f32 v[116:117], v[116:117], v[186:187]
	v_pk_add_f32 v[122:123], v[122:123], v[170:171]
	v_pk_add_f32 v[120:121], v[120:121], v[182:183]
	v_pk_add_f32 v[168:169], v[114:115], v[176:177]
	v_pk_add_f32 v[170:171], v[112:113], v[188:189]
	v_mul_f32_e32 v114, v125, v125
	v_mul_f32_e32 v115, v127, v127
	v_cvt_pk_bf16_f32 v112, v124, v125
	v_cvt_pk_bf16_f32 v113, v126, v127
	v_mul_f32_e32 v125, v117, v117
	v_mul_f32_e32 v127, v119, v119
	v_mul_f32_e32 v174, v121, v121
	v_mul_f32_e32 v176, v171, v171
	v_fmac_f32_e32 v114, v124, v124
	v_fmac_f32_e32 v115, v126, v126
	v_fmac_f32_e32 v125, v116, v116
	v_fmac_f32_e32 v127, v118, v118
	v_mul_f32_e32 v175, v123, v123
	v_mul_f32_e32 v177, v169, v169
	v_fmac_f32_e32 v174, v120, v120
	v_fmac_f32_e32 v176, v170, v170
	v_add_f32_e32 v114, v114, v115
	v_add_f32_e32 v115, v125, v127
	v_fmac_f32_e32 v175, v122, v122
	v_fmac_f32_e32 v177, v168, v168
	v_add_f32_e32 v114, v174, v114
	v_add_f32_e32 v115, v176, v115
	v_add_f32_e32 v114, v175, v114
	v_add_f32_e32 v115, v177, v115
	v_add_f32_e32 v124, v114, v115
	ds_bpermute_b32 v125, v167, v124
	v_cvt_pk_bf16_f32 v114, v120, v121
	v_cvt_pk_bf16_f32 v115, v122, v123
	global_store_dwordx4 v[178:179], v[112:115], off
	v_lshlrev_b32_e32 v122, 2, v173
	s_waitcnt lgkmcnt(0)
	v_add_f32_e32 v112, v124, v125
	ds_bpermute_b32 v113, v122, v112
	v_cvt_pk_bf16_f32 v114, v116, v117
	v_cvt_pk_bf16_f32 v115, v118, v119
	v_cvt_pk_bf16_f32 v116, v170, v171
	v_cvt_pk_bf16_f32 v117, v168, v169
	global_store_dwordx4 v[178:179], v[114:117], off offset:256
	s_and_saveexec_b64 s[20:21], s[6:7]
	s_cbranch_execz .LBB0_984
	v_lshl_add_u64 v[114:115], v[156:157], 2, s[72:73]
	s_waitcnt lgkmcnt(0)
	v_add_f32_e32 v112, v112, v113
	global_atomic_add_f32 v[114:115], v112, off
